# v20: v14 + NA chunks issue each tile-half's PV MFMAs right after its exp/cvt (PV interleaved into the softmax) instead of after all three tiles
# speedup vs baseline: 1.0111x; 1.0047x over previous
.Lna_unit:
	s_lshr_b32 s54, s21, 6
	s_and_b32 s55, s21, 63
	s_lshr_b32 s56, s54, 4
	s_and_b32 s57, s54, 15
	s_lshl_b32 s58, s55, 2
	s_add_i32 s59, s58, -4
	s_max_i32 s59, s59, 0
	s_min_i32 s59, s59, 0xf8
	s_lshl_b32 s25, s30, 1
	s_add_i32 s25, s25, s58
	s_add_i32 s23, s25, -4
	s_max_i32 s23, s23, 0
	s_min_i32 s23, s23, 0xf8
	s_sub_i32 s24, s23, s59
	s_lshl_b32 s60, s56, 25
	s_lshl_b32 s61, s57, 7
	s_add_i32 s60, s60, s61
	s_add_u32 s16, s94, 0x17800000
	s_addc_u32 s17, s95, 0
	s_add_u32 s16, s16, s60
	s_addc_u32 s17, s17, 0
	v_lshrrev_b32_e32 v206, 4, v196
	v_add_u32_e32 v206, s25, v206
	v_add_u32_e32 v207, -4, v206
	v_med3_i32 v207, v207, 0, s18
	v_lshl_add_u32 v208, v206, 6, v198
	v_mov_b32_e32 v209, 0xf149f2ca
	s_waitcnt vmcnt(8)
	v_mul_f32_e32 v194, s13, v194
	v_cmp_eq_u32_e32 vcc, 1, v249
	s_nop 1
	v_cndmask_b32_e32 v194, 0, v194, vcc
	v_cmp_eq_u32_e32 vcc, 2, v249
	s_nop 1
	v_cndmask_b32_e32 v194, v194, v229, vcc
	v_mul_f32_e32 v195, s13, v195
	v_cmp_eq_u32_e32 vcc, 1, v250
	s_nop 1
	v_cndmask_b32_e32 v195, 0, v195, vcc
	v_cmp_eq_u32_e32 vcc, 2, v250
	s_nop 1
	v_cndmask_b32_e32 v195, v195, v229, vcc
	s_barrier
	ds_write_b128 v202, v[146:149]
	ds_write_b128 v202, v[150:153] offset:9216
	ds_write_b128 v202, v[154:157] offset:18432
	ds_write_b128 v202, v[158:161] offset:27648
	ds_write_b128 v202, v[162:165] offset:36864
	ds_write_b128 v202, v[166:169] offset:46080
	ds_write_b128 v203, v[170:173]
	ds_write_b128 v203, v[174:177] offset:9216
	ds_write_b128 v203, v[178:181] offset:18432
	ds_write_b128 v203, v[182:185] offset:27648
	ds_write_b128 v203, v[186:189] offset:36864
	ds_write_b128 v203, v[190:193] offset:46080
	ds_write_b32 v245, v194
	ds_write_b32 v246, v195
	s_waitcnt lgkmcnt(0)
	s_barrier
	s_waitcnt vmcnt(4)
	s_add_i32 s27, s22, 6
	s_min_i32 s27, s27, 0xff
	s_mul_i32 s27, s27, 0x60000
	v_add_u32_e32 v223, s27, v231
	global_load_dwordx4 v[146:149], v223, s[34:35]
	global_load_dwordx4 v[150:153], v223, s[36:37]
	s_add_i32 s27, s22, 7
	s_min_i32 s27, s27, 0xff
	s_mul_i32 s27, s27, 0x60000
	v_add_u32_e32 v224, s27, v231
	global_load_dwordx4 v[154:157], v224, s[34:35]
	global_load_dwordx4 v[158:161], v224, s[36:37]
	s_add_i32 s27, s22, 8
	s_min_i32 s27, s27, 0xff
	s_mul_i32 s27, s27, 0x60000
	v_add_u32_e32 v225, s27, v231
	global_load_dwordx4 v[162:165], v225, s[34:35]
	global_load_dwordx4 v[166:169], v225, s[36:37]
	s_add_i32 s27, s22, 9
	s_min_i32 s27, s27, 0xff
	s_mul_i32 s27, s27, 0x60000
	v_add_u32_e32 v226, s27, v231
	global_load_dwordx4 v[170:173], v226, s[34:35]
	global_load_dwordx4 v[174:177], v226, s[36:37]
	s_add_i32 s27, s22, 10
	s_min_i32 s27, s27, 0xff
	s_mul_i32 s27, s27, 0x60000
	v_add_u32_e32 v227, s27, v231
	global_load_dwordx4 v[178:181], v227, s[34:35]
	global_load_dwordx4 v[182:185], v227, s[36:37]
	s_cmp_lg_u32 s24, 0
	s_cbranch_scc1 .Lna_p1_d2
	s_nop 7
	s_nop 4
	ds_read_b128 v[114:117], v200
	ds_read_b128 v[118:121], v200 offset:32
	ds_read_b128 v[122:125], v200 offset:64
	ds_read_b128 v[126:129], v200 offset:96
	ds_read_b128 v[130:133], v200 offset:18432
	ds_read_b128 v[134:137], v200 offset:18464
	ds_read_b128 v[138:141], v200 offset:18496
	ds_read_b128 v[142:145], v200 offset:18528
	s_waitcnt lgkmcnt(7)
	v_mfma_f32_32x32x16_bf16 v[2:17], v[114:117], v[82:85], v[98:113]
	s_waitcnt lgkmcnt(6)
	v_mfma_f32_32x32x16_bf16 v[2:17], v[118:121], v[86:89], v[2:17]
	s_waitcnt lgkmcnt(5)
	v_mfma_f32_32x32x16_bf16 v[2:17], v[122:125], v[90:93], v[2:17]
	s_waitcnt lgkmcnt(4)
	v_mfma_f32_32x32x16_bf16 v[2:17], v[126:129], v[94:97], v[2:17]
	ds_read_b128 v[114:117], v200 offset:36864
	ds_read_b128 v[118:121], v200 offset:36896
	ds_read_b128 v[122:125], v200 offset:36928
	ds_read_b128 v[126:129], v200 offset:36960
	s_waitcnt lgkmcnt(7)
	v_mfma_f32_32x32x16_bf16 v[18:33], v[130:133], v[82:85], v[98:113]
	s_waitcnt lgkmcnt(6)
	v_mfma_f32_32x32x16_bf16 v[18:33], v[134:137], v[86:89], v[18:33]
	s_waitcnt lgkmcnt(5)
	v_mfma_f32_32x32x16_bf16 v[18:33], v[138:141], v[90:93], v[18:33]
	s_waitcnt lgkmcnt(4)
	v_mfma_f32_32x32x16_bf16 v[18:33], v[142:145], v[94:97], v[18:33]
	s_waitcnt lgkmcnt(3)
	v_mfma_f32_32x32x16_bf16 v[34:49], v[114:117], v[82:85], v[98:113]
	s_waitcnt lgkmcnt(2)
	v_mfma_f32_32x32x16_bf16 v[34:49], v[118:121], v[86:89], v[34:49]
	s_waitcnt lgkmcnt(1)
	v_mfma_f32_32x32x16_bf16 v[34:49], v[122:125], v[90:93], v[34:49]
	s_waitcnt lgkmcnt(0)
	v_mfma_f32_32x32x16_bf16 v[34:49], v[126:129], v[94:97], v[34:49]
	s_add_i32 s62, s23, 0
	s_add_i32 s64, s23, 1
	s_add_i32 s66, s23, 2
	s_add_i32 s63, s62, 7
	s_add_i32 s65, s64, 7
	s_add_i32 s67, s66, 7
	v_sub_u32_e32 v217, s63, v206
	v_sub_u32_e32 v219, s65, v206
	v_sub_u32_e32 v221, s67, v206
	v_sub_u32_e32 v218, s62, v207
	v_sub_u32_e32 v220, s64, v207
	v_sub_u32_e32 v222, s66, v207
	v_med3_i32 v217, v217, 0, 14
	v_med3_i32 v219, v219, 0, 14
	v_med3_i32 v221, v221, 0, 14
	v_cmp_gt_u32_e64 s[40:41], 8, v218
	v_cmp_gt_u32_e64 s[42:43], 8, v220
	v_cmp_gt_u32_e64 s[44:45], 8, v222
	v_mul_u32_u24_e32 v217, 31, v217
	v_mul_u32_u24_e32 v219, 31, v219
	v_mul_u32_u24_e32 v221, 31, v221
	v_add_u32_e32 v217, v217, v199
	v_add_u32_e32 v219, v219, v199
	v_add_u32_e32 v221, v221, v199
	v_lshlrev_b32_e32 v217, 2, v217
	v_lshlrev_b32_e32 v219, 2, v219
	v_lshlrev_b32_e32 v221, 2, v221
	v_add_u32_e32 v217, 110848, v217
	v_add_u32_e32 v219, 110848, v219
	v_add_u32_e32 v221, 110848, v221
	v_cndmask_b32_e64 v230, v244, v217, s[40:41]
	v_cndmask_b32_e64 v223, v244, v219, s[42:43]
	v_cndmask_b32_e64 v224, v244, v221, s[44:45]
	ds_read2_b32 v[114:115], v230 offset0:0 offset1:1
	ds_read2_b32 v[116:117], v230 offset0:2 offset1:3
	ds_read2_b32 v[118:119], v230 offset0:4 offset1:5
	ds_read2_b32 v[120:121], v230 offset0:6 offset1:7
	ds_read2_b32 v[122:123], v230 offset0:16 offset1:17
	ds_read2_b32 v[124:125], v230 offset0:18 offset1:19
	ds_read2_b32 v[126:127], v230 offset0:20 offset1:21
	ds_read2_b32 v[128:129], v230 offset0:22 offset1:23
	s_waitcnt lgkmcnt(7)
	v_fma_f32 v2, v2, s14, v114
	v_fma_f32 v3, v3, s14, v115
	s_waitcnt lgkmcnt(6)
	v_fma_f32 v4, v4, s14, v116
	v_fma_f32 v5, v5, s14, v117
	s_waitcnt lgkmcnt(5)
	v_fma_f32 v6, v6, s14, v118
	v_fma_f32 v7, v7, s14, v119
	s_waitcnt lgkmcnt(4)
	v_fma_f32 v8, v8, s14, v120
	v_fma_f32 v9, v9, s14, v121
	s_waitcnt lgkmcnt(3)
	v_fma_f32 v10, v10, s14, v122
	v_fma_f32 v11, v11, s14, v123
	s_waitcnt lgkmcnt(2)
	v_fma_f32 v12, v12, s14, v124
	v_fma_f32 v13, v13, s14, v125
	s_waitcnt lgkmcnt(1)
	v_fma_f32 v14, v14, s14, v126
	v_fma_f32 v15, v15, s14, v127
	s_waitcnt lgkmcnt(0)
	v_fma_f32 v16, v16, s14, v128
	v_fma_f32 v17, v17, s14, v129
	ds_read2_b32 v[130:131], v223 offset0:0 offset1:1
	ds_read2_b32 v[132:133], v223 offset0:2 offset1:3
	ds_read2_b32 v[134:135], v223 offset0:4 offset1:5
	ds_read2_b32 v[136:137], v223 offset0:6 offset1:7
	ds_read2_b32 v[138:139], v223 offset0:16 offset1:17
	ds_read2_b32 v[140:141], v223 offset0:18 offset1:19
	ds_read2_b32 v[142:143], v223 offset0:20 offset1:21
	ds_read2_b32 v[144:145], v223 offset0:22 offset1:23
	s_waitcnt lgkmcnt(7)
	v_fma_f32 v18, v18, s14, v130
	v_fma_f32 v19, v19, s14, v131
	s_waitcnt lgkmcnt(6)
	v_fma_f32 v20, v20, s14, v132
	v_fma_f32 v21, v21, s14, v133
	s_waitcnt lgkmcnt(5)
	v_fma_f32 v22, v22, s14, v134
	v_fma_f32 v23, v23, s14, v135
	s_waitcnt lgkmcnt(4)
	v_fma_f32 v24, v24, s14, v136
	v_fma_f32 v25, v25, s14, v137
	s_waitcnt lgkmcnt(3)
	v_fma_f32 v26, v26, s14, v138
	v_fma_f32 v27, v27, s14, v139
	s_waitcnt lgkmcnt(2)
	v_fma_f32 v28, v28, s14, v140
	v_fma_f32 v29, v29, s14, v141
	s_waitcnt lgkmcnt(1)
	v_fma_f32 v30, v30, s14, v142
	v_fma_f32 v31, v31, s14, v143
	s_waitcnt lgkmcnt(0)
	v_fma_f32 v32, v32, s14, v144
	v_fma_f32 v33, v33, s14, v145
	ds_read2_b32 v[114:115], v224 offset0:0 offset1:1
	ds_read2_b32 v[116:117], v224 offset0:2 offset1:3
	ds_read2_b32 v[118:119], v224 offset0:4 offset1:5
	ds_read2_b32 v[120:121], v224 offset0:6 offset1:7
	ds_read2_b32 v[122:123], v224 offset0:16 offset1:17
	ds_read2_b32 v[124:125], v224 offset0:18 offset1:19
	ds_read2_b32 v[126:127], v224 offset0:20 offset1:21
	ds_read2_b32 v[128:129], v224 offset0:22 offset1:23
	s_waitcnt lgkmcnt(7)
	v_fma_f32 v34, v34, s14, v114
	v_fma_f32 v35, v35, s14, v115
	s_waitcnt lgkmcnt(6)
	v_fma_f32 v36, v36, s14, v116
	v_fma_f32 v37, v37, s14, v117
	s_waitcnt lgkmcnt(5)
	v_fma_f32 v38, v38, s14, v118
	v_fma_f32 v39, v39, s14, v119
	s_waitcnt lgkmcnt(4)
	v_fma_f32 v40, v40, s14, v120
	v_fma_f32 v41, v41, s14, v121
	s_waitcnt lgkmcnt(3)
	v_fma_f32 v42, v42, s14, v122
	v_fma_f32 v43, v43, s14, v123
	s_waitcnt lgkmcnt(2)
	v_fma_f32 v44, v44, s14, v124
	v_fma_f32 v45, v45, s14, v125
	s_waitcnt lgkmcnt(1)
	v_fma_f32 v46, v46, s14, v126
	v_fma_f32 v47, v47, s14, v127
	s_waitcnt lgkmcnt(0)
	v_fma_f32 v48, v48, s14, v128
	v_fma_f32 v49, v49, s14, v129
	v_max3_f32 v210, v2, v3, v4
	v_max3_f32 v219, v5, v6, v7
	v_max3_f32 v220, v8, v9, v10
	v_max3_f32 v221, v11, v12, v13
	v_max3_f32 v210, v210, v14, v15
	v_max3_f32 v219, v219, v16, v17
	v_max3_f32 v220, v220, v18, v19
	v_max3_f32 v221, v221, v20, v21
	v_max3_f32 v210, v210, v22, v23
	v_max3_f32 v219, v219, v24, v25
	v_max3_f32 v220, v220, v26, v27
	v_max3_f32 v221, v221, v28, v29
	v_max3_f32 v210, v210, v30, v31
	v_max3_f32 v219, v219, v32, v33
	v_max3_f32 v220, v220, v34, v35
	v_max3_f32 v221, v221, v36, v37
	v_max3_f32 v210, v210, v38, v39
	v_max3_f32 v219, v219, v40, v41
	v_max3_f32 v220, v220, v42, v43
	v_max3_f32 v221, v221, v44, v45
	v_max3_f32 v210, v210, v46, v47
	v_max3_f32 v219, v219, v48, v49
	v_max_f32_e32 v210, v210, v219
	v_max_f32_e32 v220, v220, v221
	v_max_f32_e32 v210, v210, v220
	v_mov_b32_e32 v219, v210
	s_nop 1
	v_permlane32_swap_b32_e32 v210, v219
	v_max_f32_e32 v210, v210, v219
	v_max_f32_e32 v210, v210, v209
	v_mov_b32_e32 v209, v210
	v_mov_b32_e32 v213, 0
	v_mov_b32_e32 v214, 0
	v_mov_b32_e32 v215, 0
	v_mov_b32_e32 v216, 0
	ds_read_b64_tr_b16 v[114:115], v201 offset:9216
	ds_read_b64_tr_b16 v[116:117], v201 offset:9792
	ds_read_b64_tr_b16 v[118:119], v201 offset:9280
	ds_read_b64_tr_b16 v[120:121], v201 offset:9856
	ds_read_b64_tr_b16 v[122:123], v201 offset:11520
	ds_read_b64_tr_b16 v[124:125], v201 offset:12096
	ds_read_b64_tr_b16 v[126:127], v201 offset:11584
	ds_read_b64_tr_b16 v[128:129], v201 offset:12160
	v_sub_f32_e32 v2, v2, v209
	v_sub_f32_e32 v3, v3, v209
	v_sub_f32_e32 v4, v4, v209
	v_sub_f32_e32 v5, v5, v209
	v_sub_f32_e32 v6, v6, v209
	v_sub_f32_e32 v7, v7, v209
	v_sub_f32_e32 v8, v8, v209
	v_sub_f32_e32 v9, v9, v209
	v_exp_f32_e32 v2, v2
	v_exp_f32_e32 v3, v3
	v_exp_f32_e32 v4, v4
	v_exp_f32_e32 v5, v5
	v_exp_f32_e32 v6, v6
	v_exp_f32_e32 v7, v7
	v_exp_f32_e32 v8, v8
	v_exp_f32_e32 v9, v9
	v_add_f32_e32 v213, v213, v2
	v_add_f32_e32 v214, v214, v3
	v_add_f32_e32 v215, v215, v4
	v_add_f32_e32 v216, v216, v5
	v_add_f32_e32 v213, v213, v6
	v_add_f32_e32 v214, v214, v7
	v_add_f32_e32 v215, v215, v8
	v_add_f32_e32 v216, v216, v9
	v_cvt_pk_bf16_f32 v2, v2, v3
	v_cvt_pk_bf16_f32 v3, v4, v5
	v_cvt_pk_bf16_f32 v4, v6, v7
	v_cvt_pk_bf16_f32 v5, v8, v9
	ds_read_b64_tr_b16 v[130:131], v201 offset:27648
	ds_read_b64_tr_b16 v[132:133], v201 offset:28224
	ds_read_b64_tr_b16 v[134:135], v201 offset:27712
	ds_read_b64_tr_b16 v[136:137], v201 offset:28288
	s_waitcnt lgkmcnt(10)
	v_mfma_f32_32x32x16_bf16 v[50:65], v[114:117], v[2:5], 0
	s_waitcnt lgkmcnt(8)
	v_mfma_f32_32x32x16_bf16 v[66:81], v[118:121], v[2:5], 0
	v_sub_f32_e32 v10, v10, v209
	v_sub_f32_e32 v11, v11, v209
	v_sub_f32_e32 v12, v12, v209
	v_sub_f32_e32 v13, v13, v209
	v_sub_f32_e32 v14, v14, v209
	v_sub_f32_e32 v15, v15, v209
	v_sub_f32_e32 v16, v16, v209
	v_sub_f32_e32 v17, v17, v209
	v_exp_f32_e32 v10, v10
	v_exp_f32_e32 v11, v11
	v_exp_f32_e32 v12, v12
	v_exp_f32_e32 v13, v13
	v_exp_f32_e32 v14, v14
	v_exp_f32_e32 v15, v15
	v_exp_f32_e32 v16, v16
	v_exp_f32_e32 v17, v17
	v_add_f32_e32 v213, v213, v10
	v_add_f32_e32 v214, v214, v11
	v_add_f32_e32 v215, v215, v12
	v_add_f32_e32 v216, v216, v13
	v_add_f32_e32 v213, v213, v14
	v_add_f32_e32 v214, v214, v15
	v_add_f32_e32 v215, v215, v16
	v_add_f32_e32 v216, v216, v17
	v_cvt_pk_bf16_f32 v10, v10, v11
	v_cvt_pk_bf16_f32 v11, v12, v13
	v_cvt_pk_bf16_f32 v12, v14, v15
	v_cvt_pk_bf16_f32 v13, v16, v17
	ds_read_b64_tr_b16 v[138:139], v201 offset:29952
	ds_read_b64_tr_b16 v[140:141], v201 offset:30528
	ds_read_b64_tr_b16 v[142:143], v201 offset:30016
	ds_read_b64_tr_b16 v[144:145], v201 offset:30592
	s_waitcnt lgkmcnt(10)
	v_mfma_f32_32x32x16_bf16 v[50:65], v[122:125], v[10:13], v[50:65]
	s_waitcnt lgkmcnt(8)
	v_mfma_f32_32x32x16_bf16 v[66:81], v[126:129], v[10:13], v[66:81]
	v_sub_f32_e32 v18, v18, v209
	v_sub_f32_e32 v19, v19, v209
	v_sub_f32_e32 v20, v20, v209
	v_sub_f32_e32 v21, v21, v209
	v_sub_f32_e32 v22, v22, v209
	v_sub_f32_e32 v23, v23, v209
	v_sub_f32_e32 v24, v24, v209
	v_sub_f32_e32 v25, v25, v209
	v_exp_f32_e32 v18, v18
	v_exp_f32_e32 v19, v19
	v_exp_f32_e32 v20, v20
	v_exp_f32_e32 v21, v21
	v_exp_f32_e32 v22, v22
	v_exp_f32_e32 v23, v23
	v_exp_f32_e32 v24, v24
	v_exp_f32_e32 v25, v25
	v_add_f32_e32 v213, v213, v18
	v_add_f32_e32 v214, v214, v19
	v_add_f32_e32 v215, v215, v20
	v_add_f32_e32 v216, v216, v21
	v_add_f32_e32 v213, v213, v22
	v_add_f32_e32 v214, v214, v23
	v_add_f32_e32 v215, v215, v24
	v_add_f32_e32 v216, v216, v25
	v_cvt_pk_bf16_f32 v18, v18, v19
	v_cvt_pk_bf16_f32 v19, v20, v21
	v_cvt_pk_bf16_f32 v20, v22, v23
	v_cvt_pk_bf16_f32 v21, v24, v25
	ds_read_b64_tr_b16 v[114:115], v201 offset:46080
	ds_read_b64_tr_b16 v[116:117], v201 offset:46656
	ds_read_b64_tr_b16 v[118:119], v201 offset:46144
	ds_read_b64_tr_b16 v[120:121], v201 offset:46720
	s_waitcnt lgkmcnt(10)
	v_mfma_f32_32x32x16_bf16 v[50:65], v[130:133], v[18:21], v[50:65]
	s_waitcnt lgkmcnt(8)
	v_mfma_f32_32x32x16_bf16 v[66:81], v[134:137], v[18:21], v[66:81]
	v_sub_f32_e32 v26, v26, v209
	v_sub_f32_e32 v27, v27, v209
	v_sub_f32_e32 v28, v28, v209
	v_sub_f32_e32 v29, v29, v209
	v_sub_f32_e32 v30, v30, v209
	v_sub_f32_e32 v31, v31, v209
	v_sub_f32_e32 v32, v32, v209
	v_sub_f32_e32 v33, v33, v209
	v_exp_f32_e32 v26, v26
	v_exp_f32_e32 v27, v27
	v_exp_f32_e32 v28, v28
	v_exp_f32_e32 v29, v29
	v_exp_f32_e32 v30, v30
	v_exp_f32_e32 v31, v31
	v_exp_f32_e32 v32, v32
	v_exp_f32_e32 v33, v33
	v_add_f32_e32 v213, v213, v26
	v_add_f32_e32 v214, v214, v27
	v_add_f32_e32 v215, v215, v28
	v_add_f32_e32 v216, v216, v29
	v_add_f32_e32 v213, v213, v30
	v_add_f32_e32 v214, v214, v31
	v_add_f32_e32 v215, v215, v32
	v_add_f32_e32 v216, v216, v33
	v_cvt_pk_bf16_f32 v26, v26, v27
	v_cvt_pk_bf16_f32 v27, v28, v29
	v_cvt_pk_bf16_f32 v28, v30, v31
	v_cvt_pk_bf16_f32 v29, v32, v33
	ds_read_b64_tr_b16 v[122:123], v201 offset:48384
	ds_read_b64_tr_b16 v[124:125], v201 offset:48960
	ds_read_b64_tr_b16 v[126:127], v201 offset:48448
	ds_read_b64_tr_b16 v[128:129], v201 offset:49024
	s_waitcnt lgkmcnt(10)
	v_mfma_f32_32x32x16_bf16 v[50:65], v[138:141], v[26:29], v[50:65]
	s_waitcnt lgkmcnt(8)
	v_mfma_f32_32x32x16_bf16 v[66:81], v[142:145], v[26:29], v[66:81]
	v_sub_f32_e32 v34, v34, v209
	v_sub_f32_e32 v35, v35, v209
	v_sub_f32_e32 v36, v36, v209
	v_sub_f32_e32 v37, v37, v209
	v_sub_f32_e32 v38, v38, v209
	v_sub_f32_e32 v39, v39, v209
	v_sub_f32_e32 v40, v40, v209
	v_sub_f32_e32 v41, v41, v209
	v_exp_f32_e32 v34, v34
	v_exp_f32_e32 v35, v35
	v_exp_f32_e32 v36, v36
	v_exp_f32_e32 v37, v37
	v_exp_f32_e32 v38, v38
	v_exp_f32_e32 v39, v39
	v_exp_f32_e32 v40, v40
	v_exp_f32_e32 v41, v41
	v_add_f32_e32 v213, v213, v34
	v_add_f32_e32 v214, v214, v35
	v_add_f32_e32 v215, v215, v36
	v_add_f32_e32 v216, v216, v37
	v_add_f32_e32 v213, v213, v38
	v_add_f32_e32 v214, v214, v39
	v_add_f32_e32 v215, v215, v40
	v_add_f32_e32 v216, v216, v41
	v_cvt_pk_bf16_f32 v34, v34, v35
	v_cvt_pk_bf16_f32 v35, v36, v37
	v_cvt_pk_bf16_f32 v36, v38, v39
	v_cvt_pk_bf16_f32 v37, v40, v41
	s_waitcnt lgkmcnt(6)
	s_nop 0
	v_mfma_f32_32x32x16_bf16 v[50:65], v[114:117], v[34:37], v[50:65]
	s_waitcnt lgkmcnt(4)
	v_mfma_f32_32x32x16_bf16 v[66:81], v[118:121], v[34:37], v[66:81]
	v_sub_f32_e32 v42, v42, v209
	v_sub_f32_e32 v43, v43, v209
	v_sub_f32_e32 v44, v44, v209
	v_sub_f32_e32 v45, v45, v209
	v_sub_f32_e32 v46, v46, v209
	v_sub_f32_e32 v47, v47, v209
	v_sub_f32_e32 v48, v48, v209
	v_sub_f32_e32 v49, v49, v209
	v_exp_f32_e32 v42, v42
	v_exp_f32_e32 v43, v43
	v_exp_f32_e32 v44, v44
	v_exp_f32_e32 v45, v45
	v_exp_f32_e32 v46, v46
	v_exp_f32_e32 v47, v47
	v_exp_f32_e32 v48, v48
	v_exp_f32_e32 v49, v49
	v_add_f32_e32 v213, v213, v42
	v_add_f32_e32 v214, v214, v43
	v_add_f32_e32 v215, v215, v44
	v_add_f32_e32 v216, v216, v45
	v_add_f32_e32 v213, v213, v46
	v_add_f32_e32 v214, v214, v47
	v_add_f32_e32 v215, v215, v48
	v_add_f32_e32 v216, v216, v49
	v_cvt_pk_bf16_f32 v42, v42, v43
	v_cvt_pk_bf16_f32 v43, v44, v45
	v_cvt_pk_bf16_f32 v44, v46, v47
	v_cvt_pk_bf16_f32 v45, v48, v49
	s_waitcnt lgkmcnt(2)
	s_nop 0
	v_mfma_f32_32x32x16_bf16 v[50:65], v[122:125], v[42:45], v[50:65]
	s_waitcnt lgkmcnt(0)
	v_mfma_f32_32x32x16_bf16 v[66:81], v[126:129], v[42:45], v[66:81]
	v_add_f32_e32 v213, v213, v214
	v_add_f32_e32 v215, v215, v216
	v_add_f32_e32 v213, v213, v215
	v_mov_b32_e32 v212, v213
	s_nop 7
	s_nop 4
	ds_read_b128 v[114:117], v242
	ds_read_b128 v[118:121], v242 offset:32
	ds_read_b128 v[122:125], v242 offset:64
	ds_read_b128 v[126:129], v242 offset:96
	ds_read_b128 v[130:133], v242 offset:18432
	ds_read_b128 v[134:137], v242 offset:18464
	ds_read_b128 v[138:141], v242 offset:18496
	ds_read_b128 v[142:145], v242 offset:18528
	s_waitcnt lgkmcnt(7)
	v_mfma_f32_32x32x16_bf16 v[2:17], v[114:117], v[82:85], v[98:113]
	s_waitcnt lgkmcnt(6)
	v_mfma_f32_32x32x16_bf16 v[2:17], v[118:121], v[86:89], v[2:17]
	s_waitcnt lgkmcnt(5)
	v_mfma_f32_32x32x16_bf16 v[2:17], v[122:125], v[90:93], v[2:17]
	s_waitcnt lgkmcnt(4)
	v_mfma_f32_32x32x16_bf16 v[2:17], v[126:129], v[94:97], v[2:17]
	ds_read_b128 v[114:117], v242 offset:36864
	ds_read_b128 v[118:121], v242 offset:36896
	ds_read_b128 v[122:125], v242 offset:36928
	ds_read_b128 v[126:129], v242 offset:36960
	s_waitcnt lgkmcnt(7)
	v_mfma_f32_32x32x16_bf16 v[18:33], v[130:133], v[82:85], v[98:113]
	s_waitcnt lgkmcnt(6)
	v_mfma_f32_32x32x16_bf16 v[18:33], v[134:137], v[86:89], v[18:33]
	s_waitcnt lgkmcnt(5)
	v_mfma_f32_32x32x16_bf16 v[18:33], v[138:141], v[90:93], v[18:33]
	s_waitcnt lgkmcnt(4)
	v_mfma_f32_32x32x16_bf16 v[18:33], v[142:145], v[94:97], v[18:33]
	s_waitcnt lgkmcnt(3)
	v_mfma_f32_32x32x16_bf16 v[34:49], v[114:117], v[82:85], v[98:113]
	s_waitcnt lgkmcnt(2)
	v_mfma_f32_32x32x16_bf16 v[34:49], v[118:121], v[86:89], v[34:49]
	s_waitcnt lgkmcnt(1)
	v_mfma_f32_32x32x16_bf16 v[34:49], v[122:125], v[90:93], v[34:49]
	s_waitcnt lgkmcnt(0)
	v_mfma_f32_32x32x16_bf16 v[34:49], v[126:129], v[94:97], v[34:49]
	s_add_i32 s62, s23, 3
	s_add_i32 s64, s23, 4
	s_add_i32 s66, s23, 5
	s_add_i32 s63, s62, 7
	s_add_i32 s65, s64, 7
	s_add_i32 s67, s66, 7
	v_sub_u32_e32 v217, s63, v206
	v_sub_u32_e32 v219, s65, v206
	v_sub_u32_e32 v221, s67, v206
	v_sub_u32_e32 v218, s62, v207
	v_sub_u32_e32 v220, s64, v207
	v_sub_u32_e32 v222, s66, v207
	v_med3_i32 v217, v217, 0, 14
	v_med3_i32 v219, v219, 0, 14
	v_med3_i32 v221, v221, 0, 14
	v_cmp_gt_u32_e64 s[40:41], 8, v218
	v_cmp_gt_u32_e64 s[42:43], 8, v220
	v_cmp_gt_u32_e64 s[44:45], 8, v222
	v_mul_u32_u24_e32 v217, 31, v217
	v_mul_u32_u24_e32 v219, 31, v219
	v_mul_u32_u24_e32 v221, 31, v221
	v_add_u32_e32 v217, v217, v199
	v_add_u32_e32 v219, v219, v199
	v_add_u32_e32 v221, v221, v199
	v_lshlrev_b32_e32 v217, 2, v217
	v_lshlrev_b32_e32 v219, 2, v219
	v_lshlrev_b32_e32 v221, 2, v221
	v_add_u32_e32 v217, 110848, v217
	v_add_u32_e32 v219, 110848, v219
	v_add_u32_e32 v221, 110848, v221
	v_cndmask_b32_e64 v230, v244, v217, s[40:41]
	v_cndmask_b32_e64 v223, v244, v219, s[42:43]
	v_cndmask_b32_e64 v224, v244, v221, s[44:45]
	ds_read2_b32 v[114:115], v230 offset0:0 offset1:1
	ds_read2_b32 v[116:117], v230 offset0:2 offset1:3
	ds_read2_b32 v[118:119], v230 offset0:4 offset1:5
	ds_read2_b32 v[120:121], v230 offset0:6 offset1:7
	ds_read2_b32 v[122:123], v230 offset0:16 offset1:17
	ds_read2_b32 v[124:125], v230 offset0:18 offset1:19
	ds_read2_b32 v[126:127], v230 offset0:20 offset1:21
	ds_read2_b32 v[128:129], v230 offset0:22 offset1:23
	s_waitcnt lgkmcnt(7)
	v_fma_f32 v2, v2, s14, v114
	v_fma_f32 v3, v3, s14, v115
	s_waitcnt lgkmcnt(6)
	v_fma_f32 v4, v4, s14, v116
	v_fma_f32 v5, v5, s14, v117
	s_waitcnt lgkmcnt(5)
	v_fma_f32 v6, v6, s14, v118
	v_fma_f32 v7, v7, s14, v119
	s_waitcnt lgkmcnt(4)
	v_fma_f32 v8, v8, s14, v120
	v_fma_f32 v9, v9, s14, v121
	s_waitcnt lgkmcnt(3)
	v_fma_f32 v10, v10, s14, v122
	v_fma_f32 v11, v11, s14, v123
	s_waitcnt lgkmcnt(2)
	v_fma_f32 v12, v12, s14, v124
	v_fma_f32 v13, v13, s14, v125
	s_waitcnt lgkmcnt(1)
	v_fma_f32 v14, v14, s14, v126
	v_fma_f32 v15, v15, s14, v127
	s_waitcnt lgkmcnt(0)
	v_fma_f32 v16, v16, s14, v128
	v_fma_f32 v17, v17, s14, v129
	ds_read2_b32 v[130:131], v223 offset0:0 offset1:1
	ds_read2_b32 v[132:133], v223 offset0:2 offset1:3
	ds_read2_b32 v[134:135], v223 offset0:4 offset1:5
	ds_read2_b32 v[136:137], v223 offset0:6 offset1:7
	ds_read2_b32 v[138:139], v223 offset0:16 offset1:17
	ds_read2_b32 v[140:141], v223 offset0:18 offset1:19
	ds_read2_b32 v[142:143], v223 offset0:20 offset1:21
	ds_read2_b32 v[144:145], v223 offset0:22 offset1:23
	s_waitcnt lgkmcnt(7)
	v_fma_f32 v18, v18, s14, v130
	v_fma_f32 v19, v19, s14, v131
	s_waitcnt lgkmcnt(6)
	v_fma_f32 v20, v20, s14, v132
	v_fma_f32 v21, v21, s14, v133
	s_waitcnt lgkmcnt(5)
	v_fma_f32 v22, v22, s14, v134
	v_fma_f32 v23, v23, s14, v135
	s_waitcnt lgkmcnt(4)
	v_fma_f32 v24, v24, s14, v136
	v_fma_f32 v25, v25, s14, v137
	s_waitcnt lgkmcnt(3)
	v_fma_f32 v26, v26, s14, v138
	v_fma_f32 v27, v27, s14, v139
	s_waitcnt lgkmcnt(2)
	v_fma_f32 v28, v28, s14, v140
	v_fma_f32 v29, v29, s14, v141
	s_waitcnt lgkmcnt(1)
	v_fma_f32 v30, v30, s14, v142
	v_fma_f32 v31, v31, s14, v143
	s_waitcnt lgkmcnt(0)
	v_fma_f32 v32, v32, s14, v144
	v_fma_f32 v33, v33, s14, v145
	ds_read2_b32 v[114:115], v224 offset0:0 offset1:1
	ds_read2_b32 v[116:117], v224 offset0:2 offset1:3
	ds_read2_b32 v[118:119], v224 offset0:4 offset1:5
	ds_read2_b32 v[120:121], v224 offset0:6 offset1:7
	ds_read2_b32 v[122:123], v224 offset0:16 offset1:17
	ds_read2_b32 v[124:125], v224 offset0:18 offset1:19
	ds_read2_b32 v[126:127], v224 offset0:20 offset1:21
	ds_read2_b32 v[128:129], v224 offset0:22 offset1:23
	s_waitcnt lgkmcnt(7)
	v_fma_f32 v34, v34, s14, v114
	v_fma_f32 v35, v35, s14, v115
	s_waitcnt lgkmcnt(6)
	v_fma_f32 v36, v36, s14, v116
	v_fma_f32 v37, v37, s14, v117
	s_waitcnt lgkmcnt(5)
	v_fma_f32 v38, v38, s14, v118
	v_fma_f32 v39, v39, s14, v119
	s_waitcnt lgkmcnt(4)
	v_fma_f32 v40, v40, s14, v120
	v_fma_f32 v41, v41, s14, v121
	s_waitcnt lgkmcnt(3)
	v_fma_f32 v42, v42, s14, v122
	v_fma_f32 v43, v43, s14, v123
	s_waitcnt lgkmcnt(2)
	v_fma_f32 v44, v44, s14, v124
	v_fma_f32 v45, v45, s14, v125
	s_waitcnt lgkmcnt(1)
	v_fma_f32 v46, v46, s14, v126
	v_fma_f32 v47, v47, s14, v127
	s_waitcnt lgkmcnt(0)
	v_fma_f32 v48, v48, s14, v128
	v_fma_f32 v49, v49, s14, v129
	v_max3_f32 v210, v2, v3, v4
	v_max3_f32 v219, v5, v6, v7
	v_max3_f32 v220, v8, v9, v10
	v_max3_f32 v221, v11, v12, v13
	v_max3_f32 v210, v210, v14, v15
	v_max3_f32 v219, v219, v16, v17
	v_max3_f32 v220, v220, v18, v19
	v_max3_f32 v221, v221, v20, v21
	v_max3_f32 v210, v210, v22, v23
	v_max3_f32 v219, v219, v24, v25
	v_max3_f32 v220, v220, v26, v27
	v_max3_f32 v221, v221, v28, v29
	v_max3_f32 v210, v210, v30, v31
	v_max3_f32 v219, v219, v32, v33
	v_max3_f32 v220, v220, v34, v35
	v_max3_f32 v221, v221, v36, v37
	v_max3_f32 v210, v210, v38, v39
	v_max3_f32 v219, v219, v40, v41
	v_max3_f32 v220, v220, v42, v43
	v_max3_f32 v221, v221, v44, v45
	v_max3_f32 v210, v210, v46, v47
	v_max3_f32 v219, v219, v48, v49
	v_max_f32_e32 v210, v210, v219
	v_max_f32_e32 v220, v220, v221
	v_max_f32_e32 v210, v210, v220
	v_mov_b32_e32 v219, v210
	s_nop 1
	v_permlane32_swap_b32_e32 v210, v219
	v_max_f32_e32 v210, v210, v219
	v_max_f32_e32 v210, v210, v209
	v_sub_f32_e32 v211, v209, v210
	v_exp_f32_e32 v211, v211
	v_mov_b32_e32 v209, v210
	v_mul_f32_e32 v50, v50, v211
	v_mul_f32_e32 v51, v51, v211
	v_mul_f32_e32 v52, v52, v211
	v_mul_f32_e32 v53, v53, v211
	v_mul_f32_e32 v54, v54, v211
	v_mul_f32_e32 v55, v55, v211
	v_mul_f32_e32 v56, v56, v211
	v_mul_f32_e32 v57, v57, v211
	v_mul_f32_e32 v58, v58, v211
	v_mul_f32_e32 v59, v59, v211
	v_mul_f32_e32 v60, v60, v211
	v_mul_f32_e32 v61, v61, v211
	v_mul_f32_e32 v62, v62, v211
	v_mul_f32_e32 v63, v63, v211
	v_mul_f32_e32 v64, v64, v211
	v_mul_f32_e32 v65, v65, v211
	v_mul_f32_e32 v66, v66, v211
	v_mul_f32_e32 v67, v67, v211
	v_mul_f32_e32 v68, v68, v211
	v_mul_f32_e32 v69, v69, v211
	v_mul_f32_e32 v70, v70, v211
	v_mul_f32_e32 v71, v71, v211
	v_mul_f32_e32 v72, v72, v211
	v_mul_f32_e32 v73, v73, v211
	v_mul_f32_e32 v74, v74, v211
	v_mul_f32_e32 v75, v75, v211
	v_mul_f32_e32 v76, v76, v211
	v_mul_f32_e32 v77, v77, v211
	v_mul_f32_e32 v78, v78, v211
	v_mul_f32_e32 v79, v79, v211
	v_mul_f32_e32 v80, v80, v211
	v_mul_f32_e32 v81, v81, v211
	v_mul_f32_e32 v212, v212, v211
	v_mov_b32_e32 v213, 0
	v_mov_b32_e32 v214, 0
	v_mov_b32_e32 v215, 0
	v_mov_b32_e32 v216, 0
	ds_read_b64_tr_b16 v[114:115], v243 offset:9216
	ds_read_b64_tr_b16 v[116:117], v243 offset:9792
	ds_read_b64_tr_b16 v[118:119], v243 offset:9280
	ds_read_b64_tr_b16 v[120:121], v243 offset:9856
	ds_read_b64_tr_b16 v[122:123], v243 offset:11520
	ds_read_b64_tr_b16 v[124:125], v243 offset:12096
	ds_read_b64_tr_b16 v[126:127], v243 offset:11584
	ds_read_b64_tr_b16 v[128:129], v243 offset:12160
	v_sub_f32_e32 v2, v2, v209
	v_sub_f32_e32 v3, v3, v209
	v_sub_f32_e32 v4, v4, v209
	v_sub_f32_e32 v5, v5, v209
	v_sub_f32_e32 v6, v6, v209
	v_sub_f32_e32 v7, v7, v209
	v_sub_f32_e32 v8, v8, v209
	v_sub_f32_e32 v9, v9, v209
	v_exp_f32_e32 v2, v2
	v_exp_f32_e32 v3, v3
	v_exp_f32_e32 v4, v4
	v_exp_f32_e32 v5, v5
	v_exp_f32_e32 v6, v6
	v_exp_f32_e32 v7, v7
	v_exp_f32_e32 v8, v8
	v_exp_f32_e32 v9, v9
	v_add_f32_e32 v213, v213, v2
	v_add_f32_e32 v214, v214, v3
	v_add_f32_e32 v215, v215, v4
	v_add_f32_e32 v216, v216, v5
	v_add_f32_e32 v213, v213, v6
	v_add_f32_e32 v214, v214, v7
	v_add_f32_e32 v215, v215, v8
	v_add_f32_e32 v216, v216, v9
	v_cvt_pk_bf16_f32 v2, v2, v3
	v_cvt_pk_bf16_f32 v3, v4, v5
	v_cvt_pk_bf16_f32 v4, v6, v7
	v_cvt_pk_bf16_f32 v5, v8, v9
	ds_read_b64_tr_b16 v[130:131], v243 offset:27648
	ds_read_b64_tr_b16 v[132:133], v243 offset:28224
	ds_read_b64_tr_b16 v[134:135], v243 offset:27712
	ds_read_b64_tr_b16 v[136:137], v243 offset:28288
	s_waitcnt lgkmcnt(10)
	v_mfma_f32_32x32x16_bf16 v[50:65], v[114:117], v[2:5], v[50:65]
	s_waitcnt lgkmcnt(8)
	v_mfma_f32_32x32x16_bf16 v[66:81], v[118:121], v[2:5], v[66:81]
	v_sub_f32_e32 v10, v10, v209
	v_sub_f32_e32 v11, v11, v209
	v_sub_f32_e32 v12, v12, v209
	v_sub_f32_e32 v13, v13, v209
	v_sub_f32_e32 v14, v14, v209
	v_sub_f32_e32 v15, v15, v209
	v_sub_f32_e32 v16, v16, v209
	v_sub_f32_e32 v17, v17, v209
	v_exp_f32_e32 v10, v10
	v_exp_f32_e32 v11, v11
	v_exp_f32_e32 v12, v12
	v_exp_f32_e32 v13, v13
	v_exp_f32_e32 v14, v14
	v_exp_f32_e32 v15, v15
	v_exp_f32_e32 v16, v16
	v_exp_f32_e32 v17, v17
	v_add_f32_e32 v213, v213, v10
	v_add_f32_e32 v214, v214, v11
	v_add_f32_e32 v215, v215, v12
	v_add_f32_e32 v216, v216, v13
	v_add_f32_e32 v213, v213, v14
	v_add_f32_e32 v214, v214, v15
	v_add_f32_e32 v215, v215, v16
	v_add_f32_e32 v216, v216, v17
	v_cvt_pk_bf16_f32 v10, v10, v11
	v_cvt_pk_bf16_f32 v11, v12, v13
	v_cvt_pk_bf16_f32 v12, v14, v15
	v_cvt_pk_bf16_f32 v13, v16, v17
	ds_read_b64_tr_b16 v[138:139], v243 offset:29952
	ds_read_b64_tr_b16 v[140:141], v243 offset:30528
	ds_read_b64_tr_b16 v[142:143], v243 offset:30016
	ds_read_b64_tr_b16 v[144:145], v243 offset:30592
	s_waitcnt lgkmcnt(10)
	v_mfma_f32_32x32x16_bf16 v[50:65], v[122:125], v[10:13], v[50:65]
	s_waitcnt lgkmcnt(8)
	v_mfma_f32_32x32x16_bf16 v[66:81], v[126:129], v[10:13], v[66:81]
	v_sub_f32_e32 v18, v18, v209
	v_sub_f32_e32 v19, v19, v209
	v_sub_f32_e32 v20, v20, v209
	v_sub_f32_e32 v21, v21, v209
	v_sub_f32_e32 v22, v22, v209
	v_sub_f32_e32 v23, v23, v209
	v_sub_f32_e32 v24, v24, v209
	v_sub_f32_e32 v25, v25, v209
	v_exp_f32_e32 v18, v18
	v_exp_f32_e32 v19, v19
	v_exp_f32_e32 v20, v20
	v_exp_f32_e32 v21, v21
	v_exp_f32_e32 v22, v22
	v_exp_f32_e32 v23, v23
	v_exp_f32_e32 v24, v24
	v_exp_f32_e32 v25, v25
	v_add_f32_e32 v213, v213, v18
	v_add_f32_e32 v214, v214, v19
	v_add_f32_e32 v215, v215, v20
	v_add_f32_e32 v216, v216, v21
	v_add_f32_e32 v213, v213, v22
	v_add_f32_e32 v214, v214, v23
	v_add_f32_e32 v215, v215, v24
	v_add_f32_e32 v216, v216, v25
	v_cvt_pk_bf16_f32 v18, v18, v19
	v_cvt_pk_bf16_f32 v19, v20, v21
	v_cvt_pk_bf16_f32 v20, v22, v23
	v_cvt_pk_bf16_f32 v21, v24, v25
	ds_read_b64_tr_b16 v[114:115], v243 offset:46080
	ds_read_b64_tr_b16 v[116:117], v243 offset:46656
	ds_read_b64_tr_b16 v[118:119], v243 offset:46144
	ds_read_b64_tr_b16 v[120:121], v243 offset:46720
	s_waitcnt lgkmcnt(10)
	v_mfma_f32_32x32x16_bf16 v[50:65], v[130:133], v[18:21], v[50:65]
	s_waitcnt lgkmcnt(8)
	v_mfma_f32_32x32x16_bf16 v[66:81], v[134:137], v[18:21], v[66:81]
	v_sub_f32_e32 v26, v26, v209
	v_sub_f32_e32 v27, v27, v209
	v_sub_f32_e32 v28, v28, v209
	v_sub_f32_e32 v29, v29, v209
	v_sub_f32_e32 v30, v30, v209
	v_sub_f32_e32 v31, v31, v209
	v_sub_f32_e32 v32, v32, v209
	v_sub_f32_e32 v33, v33, v209
	v_exp_f32_e32 v26, v26
	v_exp_f32_e32 v27, v27
	v_exp_f32_e32 v28, v28
	v_exp_f32_e32 v29, v29
	v_exp_f32_e32 v30, v30
	v_exp_f32_e32 v31, v31
	v_exp_f32_e32 v32, v32
	v_exp_f32_e32 v33, v33
	v_add_f32_e32 v213, v213, v26
	v_add_f32_e32 v214, v214, v27
	v_add_f32_e32 v215, v215, v28
	v_add_f32_e32 v216, v216, v29
	v_add_f32_e32 v213, v213, v30
	v_add_f32_e32 v214, v214, v31
	v_add_f32_e32 v215, v215, v32
	v_add_f32_e32 v216, v216, v33
	v_cvt_pk_bf16_f32 v26, v26, v27
	v_cvt_pk_bf16_f32 v27, v28, v29
	v_cvt_pk_bf16_f32 v28, v30, v31
	v_cvt_pk_bf16_f32 v29, v32, v33
	ds_read_b64_tr_b16 v[122:123], v243 offset:48384
	ds_read_b64_tr_b16 v[124:125], v243 offset:48960
	ds_read_b64_tr_b16 v[126:127], v243 offset:48448
	ds_read_b64_tr_b16 v[128:129], v243 offset:49024
	s_waitcnt lgkmcnt(10)
	v_mfma_f32_32x32x16_bf16 v[50:65], v[138:141], v[26:29], v[50:65]
	s_waitcnt lgkmcnt(8)
	v_mfma_f32_32x32x16_bf16 v[66:81], v[142:145], v[26:29], v[66:81]
	v_sub_f32_e32 v34, v34, v209
	v_sub_f32_e32 v35, v35, v209
	v_sub_f32_e32 v36, v36, v209
	v_sub_f32_e32 v37, v37, v209
	v_sub_f32_e32 v38, v38, v209
	v_sub_f32_e32 v39, v39, v209
	v_sub_f32_e32 v40, v40, v209
	v_sub_f32_e32 v41, v41, v209
	v_exp_f32_e32 v34, v34
	v_exp_f32_e32 v35, v35
	v_exp_f32_e32 v36, v36
	v_exp_f32_e32 v37, v37
	v_exp_f32_e32 v38, v38
	v_exp_f32_e32 v39, v39
	v_exp_f32_e32 v40, v40
	v_exp_f32_e32 v41, v41
	v_add_f32_e32 v213, v213, v34
	v_add_f32_e32 v214, v214, v35
	v_add_f32_e32 v215, v215, v36
	v_add_f32_e32 v216, v216, v37
	v_add_f32_e32 v213, v213, v38
	v_add_f32_e32 v214, v214, v39
	v_add_f32_e32 v215, v215, v40
	v_add_f32_e32 v216, v216, v41
	v_cvt_pk_bf16_f32 v34, v34, v35
	v_cvt_pk_bf16_f32 v35, v36, v37
	v_cvt_pk_bf16_f32 v36, v38, v39
	v_cvt_pk_bf16_f32 v37, v40, v41
	s_waitcnt lgkmcnt(6)
	s_nop 0
	v_mfma_f32_32x32x16_bf16 v[50:65], v[114:117], v[34:37], v[50:65]
	s_waitcnt lgkmcnt(4)
	v_mfma_f32_32x32x16_bf16 v[66:81], v[118:121], v[34:37], v[66:81]
	v_sub_f32_e32 v42, v42, v209
	v_sub_f32_e32 v43, v43, v209
	v_sub_f32_e32 v44, v44, v209
	v_sub_f32_e32 v45, v45, v209
	v_sub_f32_e32 v46, v46, v209
	v_sub_f32_e32 v47, v47, v209
	v_sub_f32_e32 v48, v48, v209
	v_sub_f32_e32 v49, v49, v209
	v_exp_f32_e32 v42, v42
	v_exp_f32_e32 v43, v43
	v_exp_f32_e32 v44, v44
	v_exp_f32_e32 v45, v45
	v_exp_f32_e32 v46, v46
	v_exp_f32_e32 v47, v47
	v_exp_f32_e32 v48, v48
	v_exp_f32_e32 v49, v49
	v_add_f32_e32 v213, v213, v42
	v_add_f32_e32 v214, v214, v43
	v_add_f32_e32 v215, v215, v44
	v_add_f32_e32 v216, v216, v45
	v_add_f32_e32 v213, v213, v46
	v_add_f32_e32 v214, v214, v47
	v_add_f32_e32 v215, v215, v48
	v_add_f32_e32 v216, v216, v49
	v_cvt_pk_bf16_f32 v42, v42, v43
	v_cvt_pk_bf16_f32 v43, v44, v45
	v_cvt_pk_bf16_f32 v44, v46, v47
	v_cvt_pk_bf16_f32 v45, v48, v49
	s_waitcnt lgkmcnt(2)
	s_nop 0
	v_mfma_f32_32x32x16_bf16 v[50:65], v[122:125], v[42:45], v[50:65]
	s_waitcnt lgkmcnt(0)
	v_mfma_f32_32x32x16_bf16 v[66:81], v[126:129], v[42:45], v[66:81]
	v_add_f32_e32 v213, v213, v214
	v_add_f32_e32 v215, v215, v216
	v_add_f32_e32 v213, v213, v215
	v_add_f32_e32 v212, v212, v213
	s_branch .Lna_p1_end
.Lna_p1_d2:
	s_nop 7
	s_nop 4
	ds_read_b128 v[114:117], v200 offset:36864
	ds_read_b128 v[118:121], v200 offset:36896
	ds_read_b128 v[122:125], v200 offset:36928
	ds_read_b128 v[126:129], v200 offset:36960
	ds_read_b128 v[130:133], v242
	ds_read_b128 v[134:137], v242 offset:32
	ds_read_b128 v[138:141], v242 offset:64
	ds_read_b128 v[142:145], v242 offset:96
	s_waitcnt lgkmcnt(7)
	v_mfma_f32_32x32x16_bf16 v[2:17], v[114:117], v[82:85], v[98:113]
	s_waitcnt lgkmcnt(6)
	v_mfma_f32_32x32x16_bf16 v[2:17], v[118:121], v[86:89], v[2:17]
	s_waitcnt lgkmcnt(5)
	v_mfma_f32_32x32x16_bf16 v[2:17], v[122:125], v[90:93], v[2:17]
	s_waitcnt lgkmcnt(4)
	v_mfma_f32_32x32x16_bf16 v[2:17], v[126:129], v[94:97], v[2:17]
	ds_read_b128 v[114:117], v242 offset:18432
	ds_read_b128 v[118:121], v242 offset:18464
	ds_read_b128 v[122:125], v242 offset:18496
	ds_read_b128 v[126:129], v242 offset:18528
	s_waitcnt lgkmcnt(7)
	v_mfma_f32_32x32x16_bf16 v[18:33], v[130:133], v[82:85], v[98:113]
	s_waitcnt lgkmcnt(6)
	v_mfma_f32_32x32x16_bf16 v[18:33], v[134:137], v[86:89], v[18:33]
	s_waitcnt lgkmcnt(5)
	v_mfma_f32_32x32x16_bf16 v[18:33], v[138:141], v[90:93], v[18:33]
	s_waitcnt lgkmcnt(4)
	v_mfma_f32_32x32x16_bf16 v[18:33], v[142:145], v[94:97], v[18:33]
	s_waitcnt lgkmcnt(3)
	v_mfma_f32_32x32x16_bf16 v[34:49], v[114:117], v[82:85], v[98:113]
	s_waitcnt lgkmcnt(2)
	v_mfma_f32_32x32x16_bf16 v[34:49], v[118:121], v[86:89], v[34:49]
	s_waitcnt lgkmcnt(1)
	v_mfma_f32_32x32x16_bf16 v[34:49], v[122:125], v[90:93], v[34:49]
	s_waitcnt lgkmcnt(0)
	v_mfma_f32_32x32x16_bf16 v[34:49], v[126:129], v[94:97], v[34:49]
	s_add_i32 s62, s23, 0
	s_add_i32 s64, s23, 1
	s_add_i32 s66, s23, 2
	s_add_i32 s63, s62, 7
	s_add_i32 s65, s64, 7
	s_add_i32 s67, s66, 7
	v_sub_u32_e32 v217, s63, v206
	v_sub_u32_e32 v219, s65, v206
	v_sub_u32_e32 v221, s67, v206
	v_sub_u32_e32 v218, s62, v207
	v_sub_u32_e32 v220, s64, v207
	v_sub_u32_e32 v222, s66, v207
	v_med3_i32 v217, v217, 0, 14
	v_med3_i32 v219, v219, 0, 14
	v_med3_i32 v221, v221, 0, 14
	v_cmp_gt_u32_e64 s[40:41], 8, v218
	v_cmp_gt_u32_e64 s[42:43], 8, v220
	v_cmp_gt_u32_e64 s[44:45], 8, v222
	v_mul_u32_u24_e32 v217, 31, v217
	v_mul_u32_u24_e32 v219, 31, v219
	v_mul_u32_u24_e32 v221, 31, v221
	v_add_u32_e32 v217, v217, v199
	v_add_u32_e32 v219, v219, v199
	v_add_u32_e32 v221, v221, v199
	v_lshlrev_b32_e32 v217, 2, v217
	v_lshlrev_b32_e32 v219, 2, v219
	v_lshlrev_b32_e32 v221, 2, v221
	v_add_u32_e32 v217, 110848, v217
	v_add_u32_e32 v219, 110848, v219
	v_add_u32_e32 v221, 110848, v221
	v_cndmask_b32_e64 v230, v244, v217, s[40:41]
	v_cndmask_b32_e64 v223, v244, v219, s[42:43]
	v_cndmask_b32_e64 v224, v244, v221, s[44:45]
	ds_read2_b32 v[114:115], v230 offset0:0 offset1:1
	ds_read2_b32 v[116:117], v230 offset0:2 offset1:3
	ds_read2_b32 v[118:119], v230 offset0:4 offset1:5
	ds_read2_b32 v[120:121], v230 offset0:6 offset1:7
	ds_read2_b32 v[122:123], v230 offset0:16 offset1:17
	ds_read2_b32 v[124:125], v230 offset0:18 offset1:19
	ds_read2_b32 v[126:127], v230 offset0:20 offset1:21
	ds_read2_b32 v[128:129], v230 offset0:22 offset1:23
	s_waitcnt lgkmcnt(7)
	v_fma_f32 v2, v2, s14, v114
	v_fma_f32 v3, v3, s14, v115
	s_waitcnt lgkmcnt(6)
	v_fma_f32 v4, v4, s14, v116
	v_fma_f32 v5, v5, s14, v117
	s_waitcnt lgkmcnt(5)
	v_fma_f32 v6, v6, s14, v118
	v_fma_f32 v7, v7, s14, v119
	s_waitcnt lgkmcnt(4)
	v_fma_f32 v8, v8, s14, v120
	v_fma_f32 v9, v9, s14, v121
	s_waitcnt lgkmcnt(3)
	v_fma_f32 v10, v10, s14, v122
	v_fma_f32 v11, v11, s14, v123
	s_waitcnt lgkmcnt(2)
	v_fma_f32 v12, v12, s14, v124
	v_fma_f32 v13, v13, s14, v125
	s_waitcnt lgkmcnt(1)
	v_fma_f32 v14, v14, s14, v126
	v_fma_f32 v15, v15, s14, v127
	s_waitcnt lgkmcnt(0)
	v_fma_f32 v16, v16, s14, v128
	v_fma_f32 v17, v17, s14, v129
	ds_read2_b32 v[130:131], v223 offset0:0 offset1:1
	ds_read2_b32 v[132:133], v223 offset0:2 offset1:3
	ds_read2_b32 v[134:135], v223 offset0:4 offset1:5
	ds_read2_b32 v[136:137], v223 offset0:6 offset1:7
	ds_read2_b32 v[138:139], v223 offset0:16 offset1:17
	ds_read2_b32 v[140:141], v223 offset0:18 offset1:19
	ds_read2_b32 v[142:143], v223 offset0:20 offset1:21
	ds_read2_b32 v[144:145], v223 offset0:22 offset1:23
	s_waitcnt lgkmcnt(7)
	v_fma_f32 v18, v18, s14, v130
	v_fma_f32 v19, v19, s14, v131
	s_waitcnt lgkmcnt(6)
	v_fma_f32 v20, v20, s14, v132
	v_fma_f32 v21, v21, s14, v133
	s_waitcnt lgkmcnt(5)
	v_fma_f32 v22, v22, s14, v134
	v_fma_f32 v23, v23, s14, v135
	s_waitcnt lgkmcnt(4)
	v_fma_f32 v24, v24, s14, v136
	v_fma_f32 v25, v25, s14, v137
	s_waitcnt lgkmcnt(3)
	v_fma_f32 v26, v26, s14, v138
	v_fma_f32 v27, v27, s14, v139
	s_waitcnt lgkmcnt(2)
	v_fma_f32 v28, v28, s14, v140
	v_fma_f32 v29, v29, s14, v141
	s_waitcnt lgkmcnt(1)
	v_fma_f32 v30, v30, s14, v142
	v_fma_f32 v31, v31, s14, v143
	s_waitcnt lgkmcnt(0)
	v_fma_f32 v32, v32, s14, v144
	v_fma_f32 v33, v33, s14, v145
	ds_read2_b32 v[114:115], v224 offset0:0 offset1:1
	ds_read2_b32 v[116:117], v224 offset0:2 offset1:3
	ds_read2_b32 v[118:119], v224 offset0:4 offset1:5
	ds_read2_b32 v[120:121], v224 offset0:6 offset1:7
	ds_read2_b32 v[122:123], v224 offset0:16 offset1:17
	ds_read2_b32 v[124:125], v224 offset0:18 offset1:19
	ds_read2_b32 v[126:127], v224 offset0:20 offset1:21
	ds_read2_b32 v[128:129], v224 offset0:22 offset1:23
	s_waitcnt lgkmcnt(7)
	v_fma_f32 v34, v34, s14, v114
	v_fma_f32 v35, v35, s14, v115
	s_waitcnt lgkmcnt(6)
	v_fma_f32 v36, v36, s14, v116
	v_fma_f32 v37, v37, s14, v117
	s_waitcnt lgkmcnt(5)
	v_fma_f32 v38, v38, s14, v118
	v_fma_f32 v39, v39, s14, v119
	s_waitcnt lgkmcnt(4)
	v_fma_f32 v40, v40, s14, v120
	v_fma_f32 v41, v41, s14, v121
	s_waitcnt lgkmcnt(3)
	v_fma_f32 v42, v42, s14, v122
	v_fma_f32 v43, v43, s14, v123
	s_waitcnt lgkmcnt(2)
	v_fma_f32 v44, v44, s14, v124
	v_fma_f32 v45, v45, s14, v125
	s_waitcnt lgkmcnt(1)
	v_fma_f32 v46, v46, s14, v126
	v_fma_f32 v47, v47, s14, v127
	s_waitcnt lgkmcnt(0)
	v_fma_f32 v48, v48, s14, v128
	v_fma_f32 v49, v49, s14, v129
	v_max3_f32 v210, v2, v3, v4
	v_max3_f32 v219, v5, v6, v7
	v_max3_f32 v220, v8, v9, v10
	v_max3_f32 v221, v11, v12, v13
	v_max3_f32 v210, v210, v14, v15
	v_max3_f32 v219, v219, v16, v17
	v_max3_f32 v220, v220, v18, v19
	v_max3_f32 v221, v221, v20, v21
	v_max3_f32 v210, v210, v22, v23
	v_max3_f32 v219, v219, v24, v25
	v_max3_f32 v220, v220, v26, v27
	v_max3_f32 v221, v221, v28, v29
	v_max3_f32 v210, v210, v30, v31
	v_max3_f32 v219, v219, v32, v33
	v_max3_f32 v220, v220, v34, v35
	v_max3_f32 v221, v221, v36, v37
	v_max3_f32 v210, v210, v38, v39
	v_max3_f32 v219, v219, v40, v41
	v_max3_f32 v220, v220, v42, v43
	v_max3_f32 v221, v221, v44, v45
	v_max3_f32 v210, v210, v46, v47
	v_max3_f32 v219, v219, v48, v49
	v_max_f32_e32 v210, v210, v219
	v_max_f32_e32 v220, v220, v221
	v_max_f32_e32 v210, v210, v220
	v_mov_b32_e32 v219, v210
	s_nop 1
	v_permlane32_swap_b32_e32 v210, v219
	v_max_f32_e32 v210, v210, v219
	v_max_f32_e32 v210, v210, v209
	v_mov_b32_e32 v209, v210
	v_mov_b32_e32 v213, 0
	v_mov_b32_e32 v214, 0
	v_mov_b32_e32 v215, 0
	v_mov_b32_e32 v216, 0
	ds_read_b64_tr_b16 v[114:115], v201 offset:46080
	ds_read_b64_tr_b16 v[116:117], v201 offset:46656
	ds_read_b64_tr_b16 v[118:119], v201 offset:46144
	ds_read_b64_tr_b16 v[120:121], v201 offset:46720
	ds_read_b64_tr_b16 v[122:123], v201 offset:48384
	ds_read_b64_tr_b16 v[124:125], v201 offset:48960
	ds_read_b64_tr_b16 v[126:127], v201 offset:48448
	ds_read_b64_tr_b16 v[128:129], v201 offset:49024
	v_sub_f32_e32 v2, v2, v209
	v_sub_f32_e32 v3, v3, v209
	v_sub_f32_e32 v4, v4, v209
	v_sub_f32_e32 v5, v5, v209
	v_sub_f32_e32 v6, v6, v209
	v_sub_f32_e32 v7, v7, v209
	v_sub_f32_e32 v8, v8, v209
	v_sub_f32_e32 v9, v9, v209
	v_exp_f32_e32 v2, v2
	v_exp_f32_e32 v3, v3
	v_exp_f32_e32 v4, v4
	v_exp_f32_e32 v5, v5
	v_exp_f32_e32 v6, v6
	v_exp_f32_e32 v7, v7
	v_exp_f32_e32 v8, v8
	v_exp_f32_e32 v9, v9
	v_add_f32_e32 v213, v213, v2
	v_add_f32_e32 v214, v214, v3
	v_add_f32_e32 v215, v215, v4
	v_add_f32_e32 v216, v216, v5
	v_add_f32_e32 v213, v213, v6
	v_add_f32_e32 v214, v214, v7
	v_add_f32_e32 v215, v215, v8
	v_add_f32_e32 v216, v216, v9
	v_cvt_pk_bf16_f32 v2, v2, v3
	v_cvt_pk_bf16_f32 v3, v4, v5
	v_cvt_pk_bf16_f32 v4, v6, v7
	v_cvt_pk_bf16_f32 v5, v8, v9
	ds_read_b64_tr_b16 v[130:131], v243 offset:9216
	ds_read_b64_tr_b16 v[132:133], v243 offset:9792
	ds_read_b64_tr_b16 v[134:135], v243 offset:9280
	ds_read_b64_tr_b16 v[136:137], v243 offset:9856
	s_waitcnt lgkmcnt(10)
	v_mfma_f32_32x32x16_bf16 v[50:65], v[114:117], v[2:5], 0
	s_waitcnt lgkmcnt(8)
	v_mfma_f32_32x32x16_bf16 v[66:81], v[118:121], v[2:5], 0
	v_sub_f32_e32 v10, v10, v209
	v_sub_f32_e32 v11, v11, v209
	v_sub_f32_e32 v12, v12, v209
	v_sub_f32_e32 v13, v13, v209
	v_sub_f32_e32 v14, v14, v209
	v_sub_f32_e32 v15, v15, v209
	v_sub_f32_e32 v16, v16, v209
	v_sub_f32_e32 v17, v17, v209
	v_exp_f32_e32 v10, v10
	v_exp_f32_e32 v11, v11
	v_exp_f32_e32 v12, v12
	v_exp_f32_e32 v13, v13
	v_exp_f32_e32 v14, v14
	v_exp_f32_e32 v15, v15
	v_exp_f32_e32 v16, v16
	v_exp_f32_e32 v17, v17
	v_add_f32_e32 v213, v213, v10
	v_add_f32_e32 v214, v214, v11
	v_add_f32_e32 v215, v215, v12
	v_add_f32_e32 v216, v216, v13
	v_add_f32_e32 v213, v213, v14
	v_add_f32_e32 v214, v214, v15
	v_add_f32_e32 v215, v215, v16
	v_add_f32_e32 v216, v216, v17
	v_cvt_pk_bf16_f32 v10, v10, v11
	v_cvt_pk_bf16_f32 v11, v12, v13
	v_cvt_pk_bf16_f32 v12, v14, v15
	v_cvt_pk_bf16_f32 v13, v16, v17
	ds_read_b64_tr_b16 v[138:139], v243 offset:11520
	ds_read_b64_tr_b16 v[140:141], v243 offset:12096
	ds_read_b64_tr_b16 v[142:143], v243 offset:11584
	ds_read_b64_tr_b16 v[144:145], v243 offset:12160
	s_waitcnt lgkmcnt(10)
	v_mfma_f32_32x32x16_bf16 v[50:65], v[122:125], v[10:13], v[50:65]
	s_waitcnt lgkmcnt(8)
	v_mfma_f32_32x32x16_bf16 v[66:81], v[126:129], v[10:13], v[66:81]
	v_sub_f32_e32 v18, v18, v209
	v_sub_f32_e32 v19, v19, v209
	v_sub_f32_e32 v20, v20, v209
	v_sub_f32_e32 v21, v21, v209
	v_sub_f32_e32 v22, v22, v209
	v_sub_f32_e32 v23, v23, v209
	v_sub_f32_e32 v24, v24, v209
	v_sub_f32_e32 v25, v25, v209
	v_exp_f32_e32 v18, v18
	v_exp_f32_e32 v19, v19
	v_exp_f32_e32 v20, v20
	v_exp_f32_e32 v21, v21
	v_exp_f32_e32 v22, v22
	v_exp_f32_e32 v23, v23
	v_exp_f32_e32 v24, v24
	v_exp_f32_e32 v25, v25
	v_add_f32_e32 v213, v213, v18
	v_add_f32_e32 v214, v214, v19
	v_add_f32_e32 v215, v215, v20
	v_add_f32_e32 v216, v216, v21
	v_add_f32_e32 v213, v213, v22
	v_add_f32_e32 v214, v214, v23
	v_add_f32_e32 v215, v215, v24
	v_add_f32_e32 v216, v216, v25
	v_cvt_pk_bf16_f32 v18, v18, v19
	v_cvt_pk_bf16_f32 v19, v20, v21
	v_cvt_pk_bf16_f32 v20, v22, v23
	v_cvt_pk_bf16_f32 v21, v24, v25
	ds_read_b64_tr_b16 v[114:115], v243 offset:27648
	ds_read_b64_tr_b16 v[116:117], v243 offset:28224
	ds_read_b64_tr_b16 v[118:119], v243 offset:27712
	ds_read_b64_tr_b16 v[120:121], v243 offset:28288
	s_waitcnt lgkmcnt(10)
	v_mfma_f32_32x32x16_bf16 v[50:65], v[130:133], v[18:21], v[50:65]
	s_waitcnt lgkmcnt(8)
	v_mfma_f32_32x32x16_bf16 v[66:81], v[134:137], v[18:21], v[66:81]
	v_sub_f32_e32 v26, v26, v209
	v_sub_f32_e32 v27, v27, v209
	v_sub_f32_e32 v28, v28, v209
	v_sub_f32_e32 v29, v29, v209
	v_sub_f32_e32 v30, v30, v209
	v_sub_f32_e32 v31, v31, v209
	v_sub_f32_e32 v32, v32, v209
	v_sub_f32_e32 v33, v33, v209
	v_exp_f32_e32 v26, v26
	v_exp_f32_e32 v27, v27
	v_exp_f32_e32 v28, v28
	v_exp_f32_e32 v29, v29
	v_exp_f32_e32 v30, v30
	v_exp_f32_e32 v31, v31
	v_exp_f32_e32 v32, v32
	v_exp_f32_e32 v33, v33
	v_add_f32_e32 v213, v213, v26
	v_add_f32_e32 v214, v214, v27
	v_add_f32_e32 v215, v215, v28
	v_add_f32_e32 v216, v216, v29
	v_add_f32_e32 v213, v213, v30
	v_add_f32_e32 v214, v214, v31
	v_add_f32_e32 v215, v215, v32
	v_add_f32_e32 v216, v216, v33
	v_cvt_pk_bf16_f32 v26, v26, v27
	v_cvt_pk_bf16_f32 v27, v28, v29
	v_cvt_pk_bf16_f32 v28, v30, v31
	v_cvt_pk_bf16_f32 v29, v32, v33
	ds_read_b64_tr_b16 v[122:123], v243 offset:29952
	ds_read_b64_tr_b16 v[124:125], v243 offset:30528
	ds_read_b64_tr_b16 v[126:127], v243 offset:30016
	ds_read_b64_tr_b16 v[128:129], v243 offset:30592
	s_waitcnt lgkmcnt(10)
	v_mfma_f32_32x32x16_bf16 v[50:65], v[138:141], v[26:29], v[50:65]
	s_waitcnt lgkmcnt(8)
	v_mfma_f32_32x32x16_bf16 v[66:81], v[142:145], v[26:29], v[66:81]
	v_sub_f32_e32 v34, v34, v209
	v_sub_f32_e32 v35, v35, v209
	v_sub_f32_e32 v36, v36, v209
	v_sub_f32_e32 v37, v37, v209
	v_sub_f32_e32 v38, v38, v209
	v_sub_f32_e32 v39, v39, v209
	v_sub_f32_e32 v40, v40, v209
	v_sub_f32_e32 v41, v41, v209
	v_exp_f32_e32 v34, v34
	v_exp_f32_e32 v35, v35
	v_exp_f32_e32 v36, v36
	v_exp_f32_e32 v37, v37
	v_exp_f32_e32 v38, v38
	v_exp_f32_e32 v39, v39
	v_exp_f32_e32 v40, v40
	v_exp_f32_e32 v41, v41
	v_add_f32_e32 v213, v213, v34
	v_add_f32_e32 v214, v214, v35
	v_add_f32_e32 v215, v215, v36
	v_add_f32_e32 v216, v216, v37
	v_add_f32_e32 v213, v213, v38
	v_add_f32_e32 v214, v214, v39
	v_add_f32_e32 v215, v215, v40
	v_add_f32_e32 v216, v216, v41
	v_cvt_pk_bf16_f32 v34, v34, v35
	v_cvt_pk_bf16_f32 v35, v36, v37
	v_cvt_pk_bf16_f32 v36, v38, v39
	v_cvt_pk_bf16_f32 v37, v40, v41
	s_waitcnt lgkmcnt(6)
	s_nop 0
	v_mfma_f32_32x32x16_bf16 v[50:65], v[114:117], v[34:37], v[50:65]
	s_waitcnt lgkmcnt(4)
	v_mfma_f32_32x32x16_bf16 v[66:81], v[118:121], v[34:37], v[66:81]
	v_sub_f32_e32 v42, v42, v209
	v_sub_f32_e32 v43, v43, v209
	v_sub_f32_e32 v44, v44, v209
	v_sub_f32_e32 v45, v45, v209
	v_sub_f32_e32 v46, v46, v209
	v_sub_f32_e32 v47, v47, v209
	v_sub_f32_e32 v48, v48, v209
	v_sub_f32_e32 v49, v49, v209
	v_exp_f32_e32 v42, v42
	v_exp_f32_e32 v43, v43
	v_exp_f32_e32 v44, v44
	v_exp_f32_e32 v45, v45
	v_exp_f32_e32 v46, v46
	v_exp_f32_e32 v47, v47
	v_exp_f32_e32 v48, v48
	v_exp_f32_e32 v49, v49
	v_add_f32_e32 v213, v213, v42
	v_add_f32_e32 v214, v214, v43
	v_add_f32_e32 v215, v215, v44
	v_add_f32_e32 v216, v216, v45
	v_add_f32_e32 v213, v213, v46
	v_add_f32_e32 v214, v214, v47
	v_add_f32_e32 v215, v215, v48
	v_add_f32_e32 v216, v216, v49
	v_cvt_pk_bf16_f32 v42, v42, v43
	v_cvt_pk_bf16_f32 v43, v44, v45
	v_cvt_pk_bf16_f32 v44, v46, v47
	v_cvt_pk_bf16_f32 v45, v48, v49
	s_waitcnt lgkmcnt(2)
	s_nop 0
	v_mfma_f32_32x32x16_bf16 v[50:65], v[122:125], v[42:45], v[50:65]
	s_waitcnt lgkmcnt(0)
	v_mfma_f32_32x32x16_bf16 v[66:81], v[126:129], v[42:45], v[66:81]
	v_add_f32_e32 v213, v213, v214
	v_add_f32_e32 v215, v215, v216
	v_add_f32_e32 v213, v213, v215
	v_mov_b32_e32 v212, v213

.Lna_nopf:
	s_cmp_lg_u32 s24, 0
	s_cbranch_scc1 .Lna_p2_d2
	s_nop 7
	s_nop 4
	ds_read_b128 v[114:117], v200
	ds_read_b128 v[118:121], v200 offset:32
	ds_read_b128 v[122:125], v200 offset:64
	ds_read_b128 v[126:129], v200 offset:96
	ds_read_b128 v[130:133], v200 offset:18432
	ds_read_b128 v[134:137], v200 offset:18464
	ds_read_b128 v[138:141], v200 offset:18496
	ds_read_b128 v[142:145], v200 offset:18528
	s_waitcnt lgkmcnt(7)
	v_mfma_f32_32x32x16_bf16 v[2:17], v[114:117], v[82:85], v[98:113]
	s_waitcnt lgkmcnt(6)
	v_mfma_f32_32x32x16_bf16 v[2:17], v[118:121], v[86:89], v[2:17]
	s_waitcnt lgkmcnt(5)
	v_mfma_f32_32x32x16_bf16 v[2:17], v[122:125], v[90:93], v[2:17]
	s_waitcnt lgkmcnt(4)
	v_mfma_f32_32x32x16_bf16 v[2:17], v[126:129], v[94:97], v[2:17]
	ds_read_b128 v[114:117], v200 offset:36864
	ds_read_b128 v[118:121], v200 offset:36896
	ds_read_b128 v[122:125], v200 offset:36928
	ds_read_b128 v[126:129], v200 offset:36960
	s_waitcnt lgkmcnt(7)
	v_mfma_f32_32x32x16_bf16 v[18:33], v[130:133], v[82:85], v[98:113]
	s_waitcnt lgkmcnt(6)
	v_mfma_f32_32x32x16_bf16 v[18:33], v[134:137], v[86:89], v[18:33]
	s_waitcnt lgkmcnt(5)
	v_mfma_f32_32x32x16_bf16 v[18:33], v[138:141], v[90:93], v[18:33]
	s_waitcnt lgkmcnt(4)
	v_mfma_f32_32x32x16_bf16 v[18:33], v[142:145], v[94:97], v[18:33]
	s_waitcnt lgkmcnt(3)
	v_mfma_f32_32x32x16_bf16 v[34:49], v[114:117], v[82:85], v[98:113]
	s_waitcnt lgkmcnt(2)
	v_mfma_f32_32x32x16_bf16 v[34:49], v[118:121], v[86:89], v[34:49]
	s_waitcnt lgkmcnt(1)
	v_mfma_f32_32x32x16_bf16 v[34:49], v[122:125], v[90:93], v[34:49]
	s_waitcnt lgkmcnt(0)
	v_mfma_f32_32x32x16_bf16 v[34:49], v[126:129], v[94:97], v[34:49]
	s_add_i32 s62, s23, 6
	s_add_i32 s64, s23, 7
	s_add_i32 s66, s23, 8
	s_add_i32 s63, s62, 7
	s_add_i32 s65, s64, 7
	s_add_i32 s67, s66, 7
	v_sub_u32_e32 v217, s63, v206
	v_sub_u32_e32 v219, s65, v206
	v_sub_u32_e32 v221, s67, v206
	v_sub_u32_e32 v218, s62, v207
	v_sub_u32_e32 v220, s64, v207
	v_sub_u32_e32 v222, s66, v207
	v_med3_i32 v217, v217, 0, 14
	v_med3_i32 v219, v219, 0, 14
	v_med3_i32 v221, v221, 0, 14
	v_cmp_gt_u32_e64 s[40:41], 8, v218
	v_cmp_gt_u32_e64 s[42:43], 8, v220
	v_cmp_gt_u32_e64 s[44:45], 8, v222
	v_mul_u32_u24_e32 v217, 31, v217
	v_mul_u32_u24_e32 v219, 31, v219
	v_mul_u32_u24_e32 v221, 31, v221
	v_add_u32_e32 v217, v217, v199
	v_add_u32_e32 v219, v219, v199
	v_add_u32_e32 v221, v221, v199
	v_lshlrev_b32_e32 v217, 2, v217
	v_lshlrev_b32_e32 v219, 2, v219
	v_lshlrev_b32_e32 v221, 2, v221
	v_add_u32_e32 v217, 110848, v217
	v_add_u32_e32 v219, 110848, v219
	v_add_u32_e32 v221, 110848, v221
	v_cndmask_b32_e64 v230, v244, v217, s[40:41]
	v_cndmask_b32_e64 v223, v244, v219, s[42:43]
	v_cndmask_b32_e64 v224, v244, v221, s[44:45]
	ds_read2_b32 v[114:115], v230 offset0:0 offset1:1
	ds_read2_b32 v[116:117], v230 offset0:2 offset1:3
	ds_read2_b32 v[118:119], v230 offset0:4 offset1:5
	ds_read2_b32 v[120:121], v230 offset0:6 offset1:7
	ds_read2_b32 v[122:123], v230 offset0:16 offset1:17
	ds_read2_b32 v[124:125], v230 offset0:18 offset1:19
	ds_read2_b32 v[126:127], v230 offset0:20 offset1:21
	ds_read2_b32 v[128:129], v230 offset0:22 offset1:23
	s_waitcnt lgkmcnt(7)
	v_fma_f32 v2, v2, s14, v114
	v_fma_f32 v3, v3, s14, v115
	s_waitcnt lgkmcnt(6)
	v_fma_f32 v4, v4, s14, v116
	v_fma_f32 v5, v5, s14, v117
	s_waitcnt lgkmcnt(5)
	v_fma_f32 v6, v6, s14, v118
	v_fma_f32 v7, v7, s14, v119
	s_waitcnt lgkmcnt(4)
	v_fma_f32 v8, v8, s14, v120
	v_fma_f32 v9, v9, s14, v121
	s_waitcnt lgkmcnt(3)
	v_fma_f32 v10, v10, s14, v122
	v_fma_f32 v11, v11, s14, v123
	s_waitcnt lgkmcnt(2)
	v_fma_f32 v12, v12, s14, v124
	v_fma_f32 v13, v13, s14, v125
	s_waitcnt lgkmcnt(1)
	v_fma_f32 v14, v14, s14, v126
	v_fma_f32 v15, v15, s14, v127
	s_waitcnt lgkmcnt(0)
	v_fma_f32 v16, v16, s14, v128
	v_fma_f32 v17, v17, s14, v129
	ds_read2_b32 v[130:131], v223 offset0:0 offset1:1
	ds_read2_b32 v[132:133], v223 offset0:2 offset1:3
	ds_read2_b32 v[134:135], v223 offset0:4 offset1:5
	ds_read2_b32 v[136:137], v223 offset0:6 offset1:7
	ds_read2_b32 v[138:139], v223 offset0:16 offset1:17
	ds_read2_b32 v[140:141], v223 offset0:18 offset1:19
	ds_read2_b32 v[142:143], v223 offset0:20 offset1:21
	ds_read2_b32 v[144:145], v223 offset0:22 offset1:23
	s_waitcnt lgkmcnt(7)
	v_fma_f32 v18, v18, s14, v130
	v_fma_f32 v19, v19, s14, v131
	s_waitcnt lgkmcnt(6)
	v_fma_f32 v20, v20, s14, v132
	v_fma_f32 v21, v21, s14, v133
	s_waitcnt lgkmcnt(5)
	v_fma_f32 v22, v22, s14, v134
	v_fma_f32 v23, v23, s14, v135
	s_waitcnt lgkmcnt(4)
	v_fma_f32 v24, v24, s14, v136
	v_fma_f32 v25, v25, s14, v137
	s_waitcnt lgkmcnt(3)
	v_fma_f32 v26, v26, s14, v138
	v_fma_f32 v27, v27, s14, v139
	s_waitcnt lgkmcnt(2)
	v_fma_f32 v28, v28, s14, v140
	v_fma_f32 v29, v29, s14, v141
	s_waitcnt lgkmcnt(1)
	v_fma_f32 v30, v30, s14, v142
	v_fma_f32 v31, v31, s14, v143
	s_waitcnt lgkmcnt(0)
	v_fma_f32 v32, v32, s14, v144
	v_fma_f32 v33, v33, s14, v145
	ds_read2_b32 v[114:115], v224 offset0:0 offset1:1
	ds_read2_b32 v[116:117], v224 offset0:2 offset1:3
	ds_read2_b32 v[118:119], v224 offset0:4 offset1:5
	ds_read2_b32 v[120:121], v224 offset0:6 offset1:7
	ds_read2_b32 v[122:123], v224 offset0:16 offset1:17
	ds_read2_b32 v[124:125], v224 offset0:18 offset1:19
	ds_read2_b32 v[126:127], v224 offset0:20 offset1:21
	ds_read2_b32 v[128:129], v224 offset0:22 offset1:23
	s_waitcnt lgkmcnt(7)
	v_fma_f32 v34, v34, s14, v114
	v_fma_f32 v35, v35, s14, v115
	s_waitcnt lgkmcnt(6)
	v_fma_f32 v36, v36, s14, v116
	v_fma_f32 v37, v37, s14, v117
	s_waitcnt lgkmcnt(5)
	v_fma_f32 v38, v38, s14, v118
	v_fma_f32 v39, v39, s14, v119
	s_waitcnt lgkmcnt(4)
	v_fma_f32 v40, v40, s14, v120
	v_fma_f32 v41, v41, s14, v121
	s_waitcnt lgkmcnt(3)
	v_fma_f32 v42, v42, s14, v122
	v_fma_f32 v43, v43, s14, v123
	s_waitcnt lgkmcnt(2)
	v_fma_f32 v44, v44, s14, v124
	v_fma_f32 v45, v45, s14, v125
	s_waitcnt lgkmcnt(1)
	v_fma_f32 v46, v46, s14, v126
	v_fma_f32 v47, v47, s14, v127
	s_waitcnt lgkmcnt(0)
	v_fma_f32 v48, v48, s14, v128
	v_fma_f32 v49, v49, s14, v129
	v_max3_f32 v210, v2, v3, v4
	v_max3_f32 v219, v5, v6, v7
	v_max3_f32 v220, v8, v9, v10
	v_max3_f32 v221, v11, v12, v13
	v_max3_f32 v210, v210, v14, v15
	v_max3_f32 v219, v219, v16, v17
	v_max3_f32 v220, v220, v18, v19
	v_max3_f32 v221, v221, v20, v21
	v_max3_f32 v210, v210, v22, v23
	v_max3_f32 v219, v219, v24, v25
	v_max3_f32 v220, v220, v26, v27
	v_max3_f32 v221, v221, v28, v29
	v_max3_f32 v210, v210, v30, v31
	v_max3_f32 v219, v219, v32, v33
	v_max3_f32 v220, v220, v34, v35
	v_max3_f32 v221, v221, v36, v37
	v_max3_f32 v210, v210, v38, v39
	v_max3_f32 v219, v219, v40, v41
	v_max3_f32 v220, v220, v42, v43
	v_max3_f32 v221, v221, v44, v45
	v_max3_f32 v210, v210, v46, v47
	v_max3_f32 v219, v219, v48, v49
	v_max_f32_e32 v210, v210, v219
	v_max_f32_e32 v220, v220, v221
	v_max_f32_e32 v210, v210, v220
	v_mov_b32_e32 v219, v210
	s_nop 1
	v_permlane32_swap_b32_e32 v210, v219
	v_max_f32_e32 v210, v210, v219
	v_max_f32_e32 v210, v210, v209
	v_sub_f32_e32 v211, v209, v210
	v_exp_f32_e32 v211, v211
	v_mov_b32_e32 v209, v210
	v_mul_f32_e32 v50, v50, v211
	v_mul_f32_e32 v51, v51, v211
	v_mul_f32_e32 v52, v52, v211
	v_mul_f32_e32 v53, v53, v211
	v_mul_f32_e32 v54, v54, v211
	v_mul_f32_e32 v55, v55, v211
	v_mul_f32_e32 v56, v56, v211
	v_mul_f32_e32 v57, v57, v211
	v_mul_f32_e32 v58, v58, v211
	v_mul_f32_e32 v59, v59, v211
	v_mul_f32_e32 v60, v60, v211
	v_mul_f32_e32 v61, v61, v211
	v_mul_f32_e32 v62, v62, v211
	v_mul_f32_e32 v63, v63, v211
	v_mul_f32_e32 v64, v64, v211
	v_mul_f32_e32 v65, v65, v211
	v_mul_f32_e32 v66, v66, v211
	v_mul_f32_e32 v67, v67, v211
	v_mul_f32_e32 v68, v68, v211
	v_mul_f32_e32 v69, v69, v211
	v_mul_f32_e32 v70, v70, v211
	v_mul_f32_e32 v71, v71, v211
	v_mul_f32_e32 v72, v72, v211
	v_mul_f32_e32 v73, v73, v211
	v_mul_f32_e32 v74, v74, v211
	v_mul_f32_e32 v75, v75, v211
	v_mul_f32_e32 v76, v76, v211
	v_mul_f32_e32 v77, v77, v211
	v_mul_f32_e32 v78, v78, v211
	v_mul_f32_e32 v79, v79, v211
	v_mul_f32_e32 v80, v80, v211
	v_mul_f32_e32 v81, v81, v211
	v_mul_f32_e32 v212, v212, v211
	v_mov_b32_e32 v213, 0
	v_mov_b32_e32 v214, 0
	v_mov_b32_e32 v215, 0
	v_mov_b32_e32 v216, 0
	ds_read_b64_tr_b16 v[114:115], v201 offset:9216
	ds_read_b64_tr_b16 v[116:117], v201 offset:9792
	ds_read_b64_tr_b16 v[118:119], v201 offset:9280
	ds_read_b64_tr_b16 v[120:121], v201 offset:9856
	ds_read_b64_tr_b16 v[122:123], v201 offset:11520
	ds_read_b64_tr_b16 v[124:125], v201 offset:12096
	ds_read_b64_tr_b16 v[126:127], v201 offset:11584
	ds_read_b64_tr_b16 v[128:129], v201 offset:12160
	v_sub_f32_e32 v2, v2, v209
	v_sub_f32_e32 v3, v3, v209
	v_sub_f32_e32 v4, v4, v209
	v_sub_f32_e32 v5, v5, v209
	v_sub_f32_e32 v6, v6, v209
	v_sub_f32_e32 v7, v7, v209
	v_sub_f32_e32 v8, v8, v209
	v_sub_f32_e32 v9, v9, v209
	v_exp_f32_e32 v2, v2
	v_exp_f32_e32 v3, v3
	v_exp_f32_e32 v4, v4
	v_exp_f32_e32 v5, v5
	v_exp_f32_e32 v6, v6
	v_exp_f32_e32 v7, v7
	v_exp_f32_e32 v8, v8
	v_exp_f32_e32 v9, v9
	v_add_f32_e32 v213, v213, v2
	v_add_f32_e32 v214, v214, v3
	v_add_f32_e32 v215, v215, v4
	v_add_f32_e32 v216, v216, v5
	v_add_f32_e32 v213, v213, v6
	v_add_f32_e32 v214, v214, v7
	v_add_f32_e32 v215, v215, v8
	v_add_f32_e32 v216, v216, v9
	v_cvt_pk_bf16_f32 v2, v2, v3
	v_cvt_pk_bf16_f32 v3, v4, v5
	v_cvt_pk_bf16_f32 v4, v6, v7
	v_cvt_pk_bf16_f32 v5, v8, v9
	ds_read_b64_tr_b16 v[130:131], v201 offset:27648
	ds_read_b64_tr_b16 v[132:133], v201 offset:28224
	ds_read_b64_tr_b16 v[134:135], v201 offset:27712
	ds_read_b64_tr_b16 v[136:137], v201 offset:28288
	s_waitcnt lgkmcnt(10)
	v_mfma_f32_32x32x16_bf16 v[50:65], v[114:117], v[2:5], v[50:65]
	s_waitcnt lgkmcnt(8)
	v_mfma_f32_32x32x16_bf16 v[66:81], v[118:121], v[2:5], v[66:81]
	v_sub_f32_e32 v10, v10, v209
	v_sub_f32_e32 v11, v11, v209
	v_sub_f32_e32 v12, v12, v209
	v_sub_f32_e32 v13, v13, v209
	v_sub_f32_e32 v14, v14, v209
	v_sub_f32_e32 v15, v15, v209
	v_sub_f32_e32 v16, v16, v209
	v_sub_f32_e32 v17, v17, v209
	v_exp_f32_e32 v10, v10
	v_exp_f32_e32 v11, v11
	v_exp_f32_e32 v12, v12
	v_exp_f32_e32 v13, v13
	v_exp_f32_e32 v14, v14
	v_exp_f32_e32 v15, v15
	v_exp_f32_e32 v16, v16
	v_exp_f32_e32 v17, v17
	v_add_f32_e32 v213, v213, v10
	v_add_f32_e32 v214, v214, v11
	v_add_f32_e32 v215, v215, v12
	v_add_f32_e32 v216, v216, v13
	v_add_f32_e32 v213, v213, v14
	v_add_f32_e32 v214, v214, v15
	v_add_f32_e32 v215, v215, v16
	v_add_f32_e32 v216, v216, v17
	v_cvt_pk_bf16_f32 v10, v10, v11
	v_cvt_pk_bf16_f32 v11, v12, v13
	v_cvt_pk_bf16_f32 v12, v14, v15
	v_cvt_pk_bf16_f32 v13, v16, v17
	ds_read_b64_tr_b16 v[138:139], v201 offset:29952
	ds_read_b64_tr_b16 v[140:141], v201 offset:30528
	ds_read_b64_tr_b16 v[142:143], v201 offset:30016
	ds_read_b64_tr_b16 v[144:145], v201 offset:30592
	s_waitcnt lgkmcnt(10)
	v_mfma_f32_32x32x16_bf16 v[50:65], v[122:125], v[10:13], v[50:65]
	s_waitcnt lgkmcnt(8)
	v_mfma_f32_32x32x16_bf16 v[66:81], v[126:129], v[10:13], v[66:81]
	v_sub_f32_e32 v18, v18, v209
	v_sub_f32_e32 v19, v19, v209
	v_sub_f32_e32 v20, v20, v209
	v_sub_f32_e32 v21, v21, v209
	v_sub_f32_e32 v22, v22, v209
	v_sub_f32_e32 v23, v23, v209
	v_sub_f32_e32 v24, v24, v209
	v_sub_f32_e32 v25, v25, v209
	v_exp_f32_e32 v18, v18
	v_exp_f32_e32 v19, v19
	v_exp_f32_e32 v20, v20
	v_exp_f32_e32 v21, v21
	v_exp_f32_e32 v22, v22
	v_exp_f32_e32 v23, v23
	v_exp_f32_e32 v24, v24
	v_exp_f32_e32 v25, v25
	v_add_f32_e32 v213, v213, v18
	v_add_f32_e32 v214, v214, v19
	v_add_f32_e32 v215, v215, v20
	v_add_f32_e32 v216, v216, v21
	v_add_f32_e32 v213, v213, v22
	v_add_f32_e32 v214, v214, v23
	v_add_f32_e32 v215, v215, v24
	v_add_f32_e32 v216, v216, v25
	v_cvt_pk_bf16_f32 v18, v18, v19
	v_cvt_pk_bf16_f32 v19, v20, v21
	v_cvt_pk_bf16_f32 v20, v22, v23
	v_cvt_pk_bf16_f32 v21, v24, v25
	ds_read_b64_tr_b16 v[114:115], v201 offset:46080
	ds_read_b64_tr_b16 v[116:117], v201 offset:46656
	ds_read_b64_tr_b16 v[118:119], v201 offset:46144
	ds_read_b64_tr_b16 v[120:121], v201 offset:46720
	s_waitcnt lgkmcnt(10)
	v_mfma_f32_32x32x16_bf16 v[50:65], v[130:133], v[18:21], v[50:65]
	s_waitcnt lgkmcnt(8)
	v_mfma_f32_32x32x16_bf16 v[66:81], v[134:137], v[18:21], v[66:81]
	v_sub_f32_e32 v26, v26, v209
	v_sub_f32_e32 v27, v27, v209
	v_sub_f32_e32 v28, v28, v209
	v_sub_f32_e32 v29, v29, v209
	v_sub_f32_e32 v30, v30, v209
	v_sub_f32_e32 v31, v31, v209
	v_sub_f32_e32 v32, v32, v209
	v_sub_f32_e32 v33, v33, v209
	v_exp_f32_e32 v26, v26
	v_exp_f32_e32 v27, v27
	v_exp_f32_e32 v28, v28
	v_exp_f32_e32 v29, v29
	v_exp_f32_e32 v30, v30
	v_exp_f32_e32 v31, v31
	v_exp_f32_e32 v32, v32
	v_exp_f32_e32 v33, v33
	v_add_f32_e32 v213, v213, v26
	v_add_f32_e32 v214, v214, v27
	v_add_f32_e32 v215, v215, v28
	v_add_f32_e32 v216, v216, v29
	v_add_f32_e32 v213, v213, v30
	v_add_f32_e32 v214, v214, v31
	v_add_f32_e32 v215, v215, v32
	v_add_f32_e32 v216, v216, v33
	v_cvt_pk_bf16_f32 v26, v26, v27
	v_cvt_pk_bf16_f32 v27, v28, v29
	v_cvt_pk_bf16_f32 v28, v30, v31
	v_cvt_pk_bf16_f32 v29, v32, v33
	ds_read_b64_tr_b16 v[122:123], v201 offset:48384
	ds_read_b64_tr_b16 v[124:125], v201 offset:48960
	ds_read_b64_tr_b16 v[126:127], v201 offset:48448
	ds_read_b64_tr_b16 v[128:129], v201 offset:49024
	s_waitcnt lgkmcnt(10)
	v_mfma_f32_32x32x16_bf16 v[50:65], v[138:141], v[26:29], v[50:65]
	s_waitcnt lgkmcnt(8)
	v_mfma_f32_32x32x16_bf16 v[66:81], v[142:145], v[26:29], v[66:81]
	v_sub_f32_e32 v34, v34, v209
	v_sub_f32_e32 v35, v35, v209
	v_sub_f32_e32 v36, v36, v209
	v_sub_f32_e32 v37, v37, v209
	v_sub_f32_e32 v38, v38, v209
	v_sub_f32_e32 v39, v39, v209
	v_sub_f32_e32 v40, v40, v209
	v_sub_f32_e32 v41, v41, v209
	v_exp_f32_e32 v34, v34
	v_exp_f32_e32 v35, v35
	v_exp_f32_e32 v36, v36
	v_exp_f32_e32 v37, v37
	v_exp_f32_e32 v38, v38
	v_exp_f32_e32 v39, v39
	v_exp_f32_e32 v40, v40
	v_exp_f32_e32 v41, v41
	v_add_f32_e32 v213, v213, v34
	v_add_f32_e32 v214, v214, v35
	v_add_f32_e32 v215, v215, v36
	v_add_f32_e32 v216, v216, v37
	v_add_f32_e32 v213, v213, v38
	v_add_f32_e32 v214, v214, v39
	v_add_f32_e32 v215, v215, v40
	v_add_f32_e32 v216, v216, v41
	v_cvt_pk_bf16_f32 v34, v34, v35
	v_cvt_pk_bf16_f32 v35, v36, v37
	v_cvt_pk_bf16_f32 v36, v38, v39
	v_cvt_pk_bf16_f32 v37, v40, v41
	s_waitcnt lgkmcnt(6)
	s_nop 0
	v_mfma_f32_32x32x16_bf16 v[50:65], v[114:117], v[34:37], v[50:65]
	s_waitcnt lgkmcnt(4)
	v_mfma_f32_32x32x16_bf16 v[66:81], v[118:121], v[34:37], v[66:81]
	v_sub_f32_e32 v42, v42, v209
	v_sub_f32_e32 v43, v43, v209
	v_sub_f32_e32 v44, v44, v209
	v_sub_f32_e32 v45, v45, v209
	v_sub_f32_e32 v46, v46, v209
	v_sub_f32_e32 v47, v47, v209
	v_sub_f32_e32 v48, v48, v209
	v_sub_f32_e32 v49, v49, v209
	v_exp_f32_e32 v42, v42
	v_exp_f32_e32 v43, v43
	v_exp_f32_e32 v44, v44
	v_exp_f32_e32 v45, v45
	v_exp_f32_e32 v46, v46
	v_exp_f32_e32 v47, v47
	v_exp_f32_e32 v48, v48
	v_exp_f32_e32 v49, v49
	v_add_f32_e32 v213, v213, v42
	v_add_f32_e32 v214, v214, v43
	v_add_f32_e32 v215, v215, v44
	v_add_f32_e32 v216, v216, v45
	v_add_f32_e32 v213, v213, v46
	v_add_f32_e32 v214, v214, v47
	v_add_f32_e32 v215, v215, v48
	v_add_f32_e32 v216, v216, v49
	v_cvt_pk_bf16_f32 v42, v42, v43
	v_cvt_pk_bf16_f32 v43, v44, v45
	v_cvt_pk_bf16_f32 v44, v46, v47
	v_cvt_pk_bf16_f32 v45, v48, v49
	s_waitcnt lgkmcnt(2)
	s_nop 0
	v_mfma_f32_32x32x16_bf16 v[50:65], v[122:125], v[42:45], v[50:65]
	s_waitcnt lgkmcnt(0)
	v_mfma_f32_32x32x16_bf16 v[66:81], v[126:129], v[42:45], v[66:81]
	v_add_f32_e32 v213, v213, v214
	v_add_f32_e32 v215, v215, v216
	v_add_f32_e32 v213, v213, v215
	v_add_f32_e32 v212, v212, v213
	s_branch .Lna_p2_end
.Lna_p2_d2:
	s_nop 7
	s_nop 4
	ds_read_b128 v[114:117], v242 offset:36864
	ds_read_b128 v[118:121], v242 offset:36896
	ds_read_b128 v[122:125], v242 offset:36928
	ds_read_b128 v[126:129], v242 offset:36960
	ds_read_b128 v[130:133], v200
	ds_read_b128 v[134:137], v200 offset:32
	ds_read_b128 v[138:141], v200 offset:64
	ds_read_b128 v[142:145], v200 offset:96
	s_waitcnt lgkmcnt(7)
	v_mfma_f32_32x32x16_bf16 v[2:17], v[114:117], v[82:85], v[98:113]
	s_waitcnt lgkmcnt(6)
	v_mfma_f32_32x32x16_bf16 v[2:17], v[118:121], v[86:89], v[2:17]
	s_waitcnt lgkmcnt(5)
	v_mfma_f32_32x32x16_bf16 v[2:17], v[122:125], v[90:93], v[2:17]
	s_waitcnt lgkmcnt(4)
	v_mfma_f32_32x32x16_bf16 v[2:17], v[126:129], v[94:97], v[2:17]
	ds_read_b128 v[114:117], v200 offset:18432
	ds_read_b128 v[118:121], v200 offset:18464
	ds_read_b128 v[122:125], v200 offset:18496
	ds_read_b128 v[126:129], v200 offset:18528
	s_waitcnt lgkmcnt(7)
	v_mfma_f32_32x32x16_bf16 v[18:33], v[130:133], v[82:85], v[98:113]
	s_waitcnt lgkmcnt(6)
	v_mfma_f32_32x32x16_bf16 v[18:33], v[134:137], v[86:89], v[18:33]
	s_waitcnt lgkmcnt(5)
	v_mfma_f32_32x32x16_bf16 v[18:33], v[138:141], v[90:93], v[18:33]
	s_waitcnt lgkmcnt(4)
	v_mfma_f32_32x32x16_bf16 v[18:33], v[142:145], v[94:97], v[18:33]
	s_waitcnt lgkmcnt(3)
	v_mfma_f32_32x32x16_bf16 v[34:49], v[114:117], v[82:85], v[98:113]
	s_waitcnt lgkmcnt(2)
	v_mfma_f32_32x32x16_bf16 v[34:49], v[118:121], v[86:89], v[34:49]
	s_waitcnt lgkmcnt(1)
	v_mfma_f32_32x32x16_bf16 v[34:49], v[122:125], v[90:93], v[34:49]
	s_waitcnt lgkmcnt(0)
	v_mfma_f32_32x32x16_bf16 v[34:49], v[126:129], v[94:97], v[34:49]
	s_add_i32 s62, s23, 3
	s_add_i32 s64, s23, 4
	s_add_i32 s66, s23, 5
	s_add_i32 s63, s62, 7
	s_add_i32 s65, s64, 7
	s_add_i32 s67, s66, 7
	v_sub_u32_e32 v217, s63, v206
	v_sub_u32_e32 v219, s65, v206
	v_sub_u32_e32 v221, s67, v206
	v_sub_u32_e32 v218, s62, v207
	v_sub_u32_e32 v220, s64, v207
	v_sub_u32_e32 v222, s66, v207
	v_med3_i32 v217, v217, 0, 14
	v_med3_i32 v219, v219, 0, 14
	v_med3_i32 v221, v221, 0, 14
	v_cmp_gt_u32_e64 s[40:41], 8, v218
	v_cmp_gt_u32_e64 s[42:43], 8, v220
	v_cmp_gt_u32_e64 s[44:45], 8, v222
	v_mul_u32_u24_e32 v217, 31, v217
	v_mul_u32_u24_e32 v219, 31, v219
	v_mul_u32_u24_e32 v221, 31, v221
	v_add_u32_e32 v217, v217, v199
	v_add_u32_e32 v219, v219, v199
	v_add_u32_e32 v221, v221, v199
	v_lshlrev_b32_e32 v217, 2, v217
	v_lshlrev_b32_e32 v219, 2, v219
	v_lshlrev_b32_e32 v221, 2, v221
	v_add_u32_e32 v217, 110848, v217
	v_add_u32_e32 v219, 110848, v219
	v_add_u32_e32 v221, 110848, v221
	v_cndmask_b32_e64 v230, v244, v217, s[40:41]
	v_cndmask_b32_e64 v223, v244, v219, s[42:43]
	v_cndmask_b32_e64 v224, v244, v221, s[44:45]
	ds_read2_b32 v[114:115], v230 offset0:0 offset1:1
	ds_read2_b32 v[116:117], v230 offset0:2 offset1:3
	ds_read2_b32 v[118:119], v230 offset0:4 offset1:5
	ds_read2_b32 v[120:121], v230 offset0:6 offset1:7
	ds_read2_b32 v[122:123], v230 offset0:16 offset1:17
	ds_read2_b32 v[124:125], v230 offset0:18 offset1:19
	ds_read2_b32 v[126:127], v230 offset0:20 offset1:21
	ds_read2_b32 v[128:129], v230 offset0:22 offset1:23
	s_waitcnt lgkmcnt(7)
	v_fma_f32 v2, v2, s14, v114
	v_fma_f32 v3, v3, s14, v115
	s_waitcnt lgkmcnt(6)
	v_fma_f32 v4, v4, s14, v116
	v_fma_f32 v5, v5, s14, v117
	s_waitcnt lgkmcnt(5)
	v_fma_f32 v6, v6, s14, v118
	v_fma_f32 v7, v7, s14, v119
	s_waitcnt lgkmcnt(4)
	v_fma_f32 v8, v8, s14, v120
	v_fma_f32 v9, v9, s14, v121
	s_waitcnt lgkmcnt(3)
	v_fma_f32 v10, v10, s14, v122
	v_fma_f32 v11, v11, s14, v123
	s_waitcnt lgkmcnt(2)
	v_fma_f32 v12, v12, s14, v124
	v_fma_f32 v13, v13, s14, v125
	s_waitcnt lgkmcnt(1)
	v_fma_f32 v14, v14, s14, v126
	v_fma_f32 v15, v15, s14, v127
	s_waitcnt lgkmcnt(0)
	v_fma_f32 v16, v16, s14, v128
	v_fma_f32 v17, v17, s14, v129
	ds_read2_b32 v[130:131], v223 offset0:0 offset1:1
	ds_read2_b32 v[132:133], v223 offset0:2 offset1:3
	ds_read2_b32 v[134:135], v223 offset0:4 offset1:5
	ds_read2_b32 v[136:137], v223 offset0:6 offset1:7
	ds_read2_b32 v[138:139], v223 offset0:16 offset1:17
	ds_read2_b32 v[140:141], v223 offset0:18 offset1:19
	ds_read2_b32 v[142:143], v223 offset0:20 offset1:21
	ds_read2_b32 v[144:145], v223 offset0:22 offset1:23
	s_waitcnt lgkmcnt(7)
	v_fma_f32 v18, v18, s14, v130
	v_fma_f32 v19, v19, s14, v131
	s_waitcnt lgkmcnt(6)
	v_fma_f32 v20, v20, s14, v132
	v_fma_f32 v21, v21, s14, v133
	s_waitcnt lgkmcnt(5)
	v_fma_f32 v22, v22, s14, v134
	v_fma_f32 v23, v23, s14, v135
	s_waitcnt lgkmcnt(4)
	v_fma_f32 v24, v24, s14, v136
	v_fma_f32 v25, v25, s14, v137
	s_waitcnt lgkmcnt(3)
	v_fma_f32 v26, v26, s14, v138
	v_fma_f32 v27, v27, s14, v139
	s_waitcnt lgkmcnt(2)
	v_fma_f32 v28, v28, s14, v140
	v_fma_f32 v29, v29, s14, v141
	s_waitcnt lgkmcnt(1)
	v_fma_f32 v30, v30, s14, v142
	v_fma_f32 v31, v31, s14, v143
	s_waitcnt lgkmcnt(0)
	v_fma_f32 v32, v32, s14, v144
	v_fma_f32 v33, v33, s14, v145
	ds_read2_b32 v[114:115], v224 offset0:0 offset1:1
	ds_read2_b32 v[116:117], v224 offset0:2 offset1:3
	ds_read2_b32 v[118:119], v224 offset0:4 offset1:5
	ds_read2_b32 v[120:121], v224 offset0:6 offset1:7
	ds_read2_b32 v[122:123], v224 offset0:16 offset1:17
	ds_read2_b32 v[124:125], v224 offset0:18 offset1:19
	ds_read2_b32 v[126:127], v224 offset0:20 offset1:21
	ds_read2_b32 v[128:129], v224 offset0:22 offset1:23
	s_waitcnt lgkmcnt(7)
	v_fma_f32 v34, v34, s14, v114
	v_fma_f32 v35, v35, s14, v115
	s_waitcnt lgkmcnt(6)
	v_fma_f32 v36, v36, s14, v116
	v_fma_f32 v37, v37, s14, v117
	s_waitcnt lgkmcnt(5)
	v_fma_f32 v38, v38, s14, v118
	v_fma_f32 v39, v39, s14, v119
	s_waitcnt lgkmcnt(4)
	v_fma_f32 v40, v40, s14, v120
	v_fma_f32 v41, v41, s14, v121
	s_waitcnt lgkmcnt(3)
	v_fma_f32 v42, v42, s14, v122
	v_fma_f32 v43, v43, s14, v123
	s_waitcnt lgkmcnt(2)
	v_fma_f32 v44, v44, s14, v124
	v_fma_f32 v45, v45, s14, v125
	s_waitcnt lgkmcnt(1)
	v_fma_f32 v46, v46, s14, v126
	v_fma_f32 v47, v47, s14, v127
	s_waitcnt lgkmcnt(0)
	v_fma_f32 v48, v48, s14, v128
	v_fma_f32 v49, v49, s14, v129
	v_max3_f32 v210, v2, v3, v4
	v_max3_f32 v219, v5, v6, v7
	v_max3_f32 v220, v8, v9, v10
	v_max3_f32 v221, v11, v12, v13
	v_max3_f32 v210, v210, v14, v15
	v_max3_f32 v219, v219, v16, v17
	v_max3_f32 v220, v220, v18, v19
	v_max3_f32 v221, v221, v20, v21
	v_max3_f32 v210, v210, v22, v23
	v_max3_f32 v219, v219, v24, v25
	v_max3_f32 v220, v220, v26, v27
	v_max3_f32 v221, v221, v28, v29
	v_max3_f32 v210, v210, v30, v31
	v_max3_f32 v219, v219, v32, v33
	v_max3_f32 v220, v220, v34, v35
	v_max3_f32 v221, v221, v36, v37
	v_max3_f32 v210, v210, v38, v39
	v_max3_f32 v219, v219, v40, v41
	v_max3_f32 v220, v220, v42, v43
	v_max3_f32 v221, v221, v44, v45
	v_max3_f32 v210, v210, v46, v47
	v_max3_f32 v219, v219, v48, v49
	v_max_f32_e32 v210, v210, v219
	v_max_f32_e32 v220, v220, v221
	v_max_f32_e32 v210, v210, v220
	v_mov_b32_e32 v219, v210
	s_nop 1
	v_permlane32_swap_b32_e32 v210, v219
	v_max_f32_e32 v210, v210, v219
	v_max_f32_e32 v210, v210, v209
	v_sub_f32_e32 v211, v209, v210
	v_exp_f32_e32 v211, v211
	v_mov_b32_e32 v209, v210
	v_mul_f32_e32 v50, v50, v211
	v_mul_f32_e32 v51, v51, v211
	v_mul_f32_e32 v52, v52, v211
	v_mul_f32_e32 v53, v53, v211
	v_mul_f32_e32 v54, v54, v211
	v_mul_f32_e32 v55, v55, v211
	v_mul_f32_e32 v56, v56, v211
	v_mul_f32_e32 v57, v57, v211
	v_mul_f32_e32 v58, v58, v211
	v_mul_f32_e32 v59, v59, v211
	v_mul_f32_e32 v60, v60, v211
	v_mul_f32_e32 v61, v61, v211
	v_mul_f32_e32 v62, v62, v211
	v_mul_f32_e32 v63, v63, v211
	v_mul_f32_e32 v64, v64, v211
	v_mul_f32_e32 v65, v65, v211
	v_mul_f32_e32 v66, v66, v211
	v_mul_f32_e32 v67, v67, v211
	v_mul_f32_e32 v68, v68, v211
	v_mul_f32_e32 v69, v69, v211
	v_mul_f32_e32 v70, v70, v211
	v_mul_f32_e32 v71, v71, v211
	v_mul_f32_e32 v72, v72, v211
	v_mul_f32_e32 v73, v73, v211
	v_mul_f32_e32 v74, v74, v211
	v_mul_f32_e32 v75, v75, v211
	v_mul_f32_e32 v76, v76, v211
	v_mul_f32_e32 v77, v77, v211
	v_mul_f32_e32 v78, v78, v211
	v_mul_f32_e32 v79, v79, v211
	v_mul_f32_e32 v80, v80, v211
	v_mul_f32_e32 v81, v81, v211
	v_mul_f32_e32 v212, v212, v211
	v_mov_b32_e32 v213, 0
	v_mov_b32_e32 v214, 0
	v_mov_b32_e32 v215, 0
	v_mov_b32_e32 v216, 0
	ds_read_b64_tr_b16 v[114:115], v243 offset:46080
	ds_read_b64_tr_b16 v[116:117], v243 offset:46656
	ds_read_b64_tr_b16 v[118:119], v243 offset:46144
	ds_read_b64_tr_b16 v[120:121], v243 offset:46720
	ds_read_b64_tr_b16 v[122:123], v243 offset:48384
	ds_read_b64_tr_b16 v[124:125], v243 offset:48960
	ds_read_b64_tr_b16 v[126:127], v243 offset:48448
	ds_read_b64_tr_b16 v[128:129], v243 offset:49024
	v_sub_f32_e32 v2, v2, v209
	v_sub_f32_e32 v3, v3, v209
	v_sub_f32_e32 v4, v4, v209
	v_sub_f32_e32 v5, v5, v209
	v_sub_f32_e32 v6, v6, v209
	v_sub_f32_e32 v7, v7, v209
	v_sub_f32_e32 v8, v8, v209
	v_sub_f32_e32 v9, v9, v209
	v_exp_f32_e32 v2, v2
	v_exp_f32_e32 v3, v3
	v_exp_f32_e32 v4, v4
	v_exp_f32_e32 v5, v5
	v_exp_f32_e32 v6, v6
	v_exp_f32_e32 v7, v7
	v_exp_f32_e32 v8, v8
	v_exp_f32_e32 v9, v9
	v_add_f32_e32 v213, v213, v2
	v_add_f32_e32 v214, v214, v3
	v_add_f32_e32 v215, v215, v4
	v_add_f32_e32 v216, v216, v5
	v_add_f32_e32 v213, v213, v6
	v_add_f32_e32 v214, v214, v7
	v_add_f32_e32 v215, v215, v8
	v_add_f32_e32 v216, v216, v9
	v_cvt_pk_bf16_f32 v2, v2, v3
	v_cvt_pk_bf16_f32 v3, v4, v5
	v_cvt_pk_bf16_f32 v4, v6, v7
	v_cvt_pk_bf16_f32 v5, v8, v9
	ds_read_b64_tr_b16 v[130:131], v201 offset:9216
	ds_read_b64_tr_b16 v[132:133], v201 offset:9792
	ds_read_b64_tr_b16 v[134:135], v201 offset:9280
	ds_read_b64_tr_b16 v[136:137], v201 offset:9856
	s_waitcnt lgkmcnt(10)
	v_mfma_f32_32x32x16_bf16 v[50:65], v[114:117], v[2:5], v[50:65]
	s_waitcnt lgkmcnt(8)
	v_mfma_f32_32x32x16_bf16 v[66:81], v[118:121], v[2:5], v[66:81]
	v_sub_f32_e32 v10, v10, v209
	v_sub_f32_e32 v11, v11, v209
	v_sub_f32_e32 v12, v12, v209
	v_sub_f32_e32 v13, v13, v209
	v_sub_f32_e32 v14, v14, v209
	v_sub_f32_e32 v15, v15, v209
	v_sub_f32_e32 v16, v16, v209
	v_sub_f32_e32 v17, v17, v209
	v_exp_f32_e32 v10, v10
	v_exp_f32_e32 v11, v11
	v_exp_f32_e32 v12, v12
	v_exp_f32_e32 v13, v13
	v_exp_f32_e32 v14, v14
	v_exp_f32_e32 v15, v15
	v_exp_f32_e32 v16, v16
	v_exp_f32_e32 v17, v17
	v_add_f32_e32 v213, v213, v10
	v_add_f32_e32 v214, v214, v11
	v_add_f32_e32 v215, v215, v12
	v_add_f32_e32 v216, v216, v13
	v_add_f32_e32 v213, v213, v14
	v_add_f32_e32 v214, v214, v15
	v_add_f32_e32 v215, v215, v16
	v_add_f32_e32 v216, v216, v17
	v_cvt_pk_bf16_f32 v10, v10, v11
	v_cvt_pk_bf16_f32 v11, v12, v13
	v_cvt_pk_bf16_f32 v12, v14, v15
	v_cvt_pk_bf16_f32 v13, v16, v17
	ds_read_b64_tr_b16 v[138:139], v201 offset:11520
	ds_read_b64_tr_b16 v[140:141], v201 offset:12096
	ds_read_b64_tr_b16 v[142:143], v201 offset:11584
	ds_read_b64_tr_b16 v[144:145], v201 offset:12160
	s_waitcnt lgkmcnt(10)
	v_mfma_f32_32x32x16_bf16 v[50:65], v[122:125], v[10:13], v[50:65]
	s_waitcnt lgkmcnt(8)
	v_mfma_f32_32x32x16_bf16 v[66:81], v[126:129], v[10:13], v[66:81]
	v_sub_f32_e32 v18, v18, v209
	v_sub_f32_e32 v19, v19, v209
	v_sub_f32_e32 v20, v20, v209
	v_sub_f32_e32 v21, v21, v209
	v_sub_f32_e32 v22, v22, v209
	v_sub_f32_e32 v23, v23, v209
	v_sub_f32_e32 v24, v24, v209
	v_sub_f32_e32 v25, v25, v209
	v_exp_f32_e32 v18, v18
	v_exp_f32_e32 v19, v19
	v_exp_f32_e32 v20, v20
	v_exp_f32_e32 v21, v21
	v_exp_f32_e32 v22, v22
	v_exp_f32_e32 v23, v23
	v_exp_f32_e32 v24, v24
	v_exp_f32_e32 v25, v25
	v_add_f32_e32 v213, v213, v18
	v_add_f32_e32 v214, v214, v19
	v_add_f32_e32 v215, v215, v20
	v_add_f32_e32 v216, v216, v21
	v_add_f32_e32 v213, v213, v22
	v_add_f32_e32 v214, v214, v23
	v_add_f32_e32 v215, v215, v24
	v_add_f32_e32 v216, v216, v25
	v_cvt_pk_bf16_f32 v18, v18, v19
	v_cvt_pk_bf16_f32 v19, v20, v21
	v_cvt_pk_bf16_f32 v20, v22, v23
	v_cvt_pk_bf16_f32 v21, v24, v25
	ds_read_b64_tr_b16 v[114:115], v201 offset:27648
	ds_read_b64_tr_b16 v[116:117], v201 offset:28224
	ds_read_b64_tr_b16 v[118:119], v201 offset:27712
	ds_read_b64_tr_b16 v[120:121], v201 offset:28288
	s_waitcnt lgkmcnt(10)
	v_mfma_f32_32x32x16_bf16 v[50:65], v[130:133], v[18:21], v[50:65]
	s_waitcnt lgkmcnt(8)
	v_mfma_f32_32x32x16_bf16 v[66:81], v[134:137], v[18:21], v[66:81]
	v_sub_f32_e32 v26, v26, v209
	v_sub_f32_e32 v27, v27, v209
	v_sub_f32_e32 v28, v28, v209
	v_sub_f32_e32 v29, v29, v209
	v_sub_f32_e32 v30, v30, v209
	v_sub_f32_e32 v31, v31, v209
	v_sub_f32_e32 v32, v32, v209
	v_sub_f32_e32 v33, v33, v209
	v_exp_f32_e32 v26, v26
	v_exp_f32_e32 v27, v27
	v_exp_f32_e32 v28, v28
	v_exp_f32_e32 v29, v29
	v_exp_f32_e32 v30, v30
	v_exp_f32_e32 v31, v31
	v_exp_f32_e32 v32, v32
	v_exp_f32_e32 v33, v33
	v_add_f32_e32 v213, v213, v26
	v_add_f32_e32 v214, v214, v27
	v_add_f32_e32 v215, v215, v28
	v_add_f32_e32 v216, v216, v29
	v_add_f32_e32 v213, v213, v30
	v_add_f32_e32 v214, v214, v31
	v_add_f32_e32 v215, v215, v32
	v_add_f32_e32 v216, v216, v33
	v_cvt_pk_bf16_f32 v26, v26, v27
	v_cvt_pk_bf16_f32 v27, v28, v29
	v_cvt_pk_bf16_f32 v28, v30, v31
	v_cvt_pk_bf16_f32 v29, v32, v33
	ds_read_b64_tr_b16 v[122:123], v201 offset:29952
	ds_read_b64_tr_b16 v[124:125], v201 offset:30528
	ds_read_b64_tr_b16 v[126:127], v201 offset:30016
	ds_read_b64_tr_b16 v[128:129], v201 offset:30592
	s_waitcnt lgkmcnt(10)
	v_mfma_f32_32x32x16_bf16 v[50:65], v[138:141], v[26:29], v[50:65]
	s_waitcnt lgkmcnt(8)
	v_mfma_f32_32x32x16_bf16 v[66:81], v[142:145], v[26:29], v[66:81]
	v_sub_f32_e32 v34, v34, v209
	v_sub_f32_e32 v35, v35, v209
	v_sub_f32_e32 v36, v36, v209
	v_sub_f32_e32 v37, v37, v209
	v_sub_f32_e32 v38, v38, v209
	v_sub_f32_e32 v39, v39, v209
	v_sub_f32_e32 v40, v40, v209
	v_sub_f32_e32 v41, v41, v209
	v_exp_f32_e32 v34, v34
	v_exp_f32_e32 v35, v35
	v_exp_f32_e32 v36, v36
	v_exp_f32_e32 v37, v37
	v_exp_f32_e32 v38, v38
	v_exp_f32_e32 v39, v39
	v_exp_f32_e32 v40, v40
	v_exp_f32_e32 v41, v41
	v_add_f32_e32 v213, v213, v34
	v_add_f32_e32 v214, v214, v35
	v_add_f32_e32 v215, v215, v36
	v_add_f32_e32 v216, v216, v37
	v_add_f32_e32 v213, v213, v38
	v_add_f32_e32 v214, v214, v39
	v_add_f32_e32 v215, v215, v40
	v_add_f32_e32 v216, v216, v41
	v_cvt_pk_bf16_f32 v34, v34, v35
	v_cvt_pk_bf16_f32 v35, v36, v37
	v_cvt_pk_bf16_f32 v36, v38, v39
	v_cvt_pk_bf16_f32 v37, v40, v41
	s_waitcnt lgkmcnt(6)
	s_nop 0
	v_mfma_f32_32x32x16_bf16 v[50:65], v[114:117], v[34:37], v[50:65]
	s_waitcnt lgkmcnt(4)
	v_mfma_f32_32x32x16_bf16 v[66:81], v[118:121], v[34:37], v[66:81]
	v_sub_f32_e32 v42, v42, v209
	v_sub_f32_e32 v43, v43, v209
	v_sub_f32_e32 v44, v44, v209
	v_sub_f32_e32 v45, v45, v209
	v_sub_f32_e32 v46, v46, v209
	v_sub_f32_e32 v47, v47, v209
	v_sub_f32_e32 v48, v48, v209
	v_sub_f32_e32 v49, v49, v209
	v_exp_f32_e32 v42, v42
	v_exp_f32_e32 v43, v43
	v_exp_f32_e32 v44, v44
	v_exp_f32_e32 v45, v45
	v_exp_f32_e32 v46, v46
	v_exp_f32_e32 v47, v47
	v_exp_f32_e32 v48, v48
	v_exp_f32_e32 v49, v49
	v_add_f32_e32 v213, v213, v42
	v_add_f32_e32 v214, v214, v43
	v_add_f32_e32 v215, v215, v44
	v_add_f32_e32 v216, v216, v45
	v_add_f32_e32 v213, v213, v46
	v_add_f32_e32 v214, v214, v47
	v_add_f32_e32 v215, v215, v48
	v_add_f32_e32 v216, v216, v49
	v_cvt_pk_bf16_f32 v42, v42, v43
	v_cvt_pk_bf16_f32 v43, v44, v45
	v_cvt_pk_bf16_f32 v44, v46, v47
	v_cvt_pk_bf16_f32 v45, v48, v49
	s_waitcnt lgkmcnt(2)
	s_nop 0
	v_mfma_f32_32x32x16_bf16 v[50:65], v[122:125], v[42:45], v[50:65]
	s_waitcnt lgkmcnt(0)
	v_mfma_f32_32x32x16_bf16 v[66:81], v[126:129], v[42:45], v[66:81]
	v_add_f32_e32 v213, v213, v214
	v_add_f32_e32 v215, v215, v216
	v_add_f32_e32 v213, v213, v215
	v_add_f32_e32 v212, v212, v213
	s_nop 7
	s_nop 4
	ds_read_b128 v[114:117], v200 offset:36864
	ds_read_b128 v[118:121], v200 offset:36896
	ds_read_b128 v[122:125], v200 offset:36928
	ds_read_b128 v[126:129], v200 offset:36960
	ds_read_b128 v[130:133], v242
	ds_read_b128 v[134:137], v242 offset:32
	ds_read_b128 v[138:141], v242 offset:64
	ds_read_b128 v[142:145], v242 offset:96
	s_waitcnt lgkmcnt(7)
	v_mfma_f32_32x32x16_bf16 v[2:17], v[114:117], v[82:85], v[98:113]
	s_waitcnt lgkmcnt(6)
	v_mfma_f32_32x32x16_bf16 v[2:17], v[118:121], v[86:89], v[2:17]
	s_waitcnt lgkmcnt(5)
	v_mfma_f32_32x32x16_bf16 v[2:17], v[122:125], v[90:93], v[2:17]
	s_waitcnt lgkmcnt(4)
	v_mfma_f32_32x32x16_bf16 v[2:17], v[126:129], v[94:97], v[2:17]
	ds_read_b128 v[114:117], v242 offset:18432
	ds_read_b128 v[118:121], v242 offset:18464
	ds_read_b128 v[122:125], v242 offset:18496
	ds_read_b128 v[126:129], v242 offset:18528
	s_waitcnt lgkmcnt(7)
	v_mfma_f32_32x32x16_bf16 v[18:33], v[130:133], v[82:85], v[98:113]
	s_waitcnt lgkmcnt(6)
	v_mfma_f32_32x32x16_bf16 v[18:33], v[134:137], v[86:89], v[18:33]
	s_waitcnt lgkmcnt(5)
	v_mfma_f32_32x32x16_bf16 v[18:33], v[138:141], v[90:93], v[18:33]
	s_waitcnt lgkmcnt(4)
	v_mfma_f32_32x32x16_bf16 v[18:33], v[142:145], v[94:97], v[18:33]
	s_waitcnt lgkmcnt(3)
	v_mfma_f32_32x32x16_bf16 v[34:49], v[114:117], v[82:85], v[98:113]
	s_waitcnt lgkmcnt(2)
	v_mfma_f32_32x32x16_bf16 v[34:49], v[118:121], v[86:89], v[34:49]
	s_waitcnt lgkmcnt(1)
	v_mfma_f32_32x32x16_bf16 v[34:49], v[122:125], v[90:93], v[34:49]
	s_waitcnt lgkmcnt(0)
	v_mfma_f32_32x32x16_bf16 v[34:49], v[126:129], v[94:97], v[34:49]
	s_add_i32 s62, s23, 6
	s_add_i32 s64, s23, 7
	s_add_i32 s66, s23, 8
	s_add_i32 s63, s62, 7
	s_add_i32 s65, s64, 7
	s_add_i32 s67, s66, 7
	v_sub_u32_e32 v217, s63, v206
	v_sub_u32_e32 v219, s65, v206
	v_sub_u32_e32 v221, s67, v206
	v_sub_u32_e32 v218, s62, v207
	v_sub_u32_e32 v220, s64, v207
	v_sub_u32_e32 v222, s66, v207
	v_med3_i32 v217, v217, 0, 14
	v_med3_i32 v219, v219, 0, 14
	v_med3_i32 v221, v221, 0, 14
	v_cmp_gt_u32_e64 s[40:41], 8, v218
	v_cmp_gt_u32_e64 s[42:43], 8, v220
	v_cmp_gt_u32_e64 s[44:45], 8, v222
	v_mul_u32_u24_e32 v217, 31, v217
	v_mul_u32_u24_e32 v219, 31, v219
	v_mul_u32_u24_e32 v221, 31, v221
	v_add_u32_e32 v217, v217, v199
	v_add_u32_e32 v219, v219, v199
	v_add_u32_e32 v221, v221, v199
	v_lshlrev_b32_e32 v217, 2, v217
	v_lshlrev_b32_e32 v219, 2, v219
	v_lshlrev_b32_e32 v221, 2, v221
	v_add_u32_e32 v217, 110848, v217
	v_add_u32_e32 v219, 110848, v219
	v_add_u32_e32 v221, 110848, v221
	v_cndmask_b32_e64 v230, v244, v217, s[40:41]
	v_cndmask_b32_e64 v223, v244, v219, s[42:43]
	v_cndmask_b32_e64 v224, v244, v221, s[44:45]
	ds_read2_b32 v[114:115], v230 offset0:0 offset1:1
	ds_read2_b32 v[116:117], v230 offset0:2 offset1:3
	ds_read2_b32 v[118:119], v230 offset0:4 offset1:5
	ds_read2_b32 v[120:121], v230 offset0:6 offset1:7
	ds_read2_b32 v[122:123], v230 offset0:16 offset1:17
	ds_read2_b32 v[124:125], v230 offset0:18 offset1:19
	ds_read2_b32 v[126:127], v230 offset0:20 offset1:21
	ds_read2_b32 v[128:129], v230 offset0:22 offset1:23
	s_waitcnt lgkmcnt(7)
	v_fma_f32 v2, v2, s14, v114
	v_fma_f32 v3, v3, s14, v115
	s_waitcnt lgkmcnt(6)
	v_fma_f32 v4, v4, s14, v116
	v_fma_f32 v5, v5, s14, v117
	s_waitcnt lgkmcnt(5)
	v_fma_f32 v6, v6, s14, v118
	v_fma_f32 v7, v7, s14, v119
	s_waitcnt lgkmcnt(4)
	v_fma_f32 v8, v8, s14, v120
	v_fma_f32 v9, v9, s14, v121
	s_waitcnt lgkmcnt(3)
	v_fma_f32 v10, v10, s14, v122
	v_fma_f32 v11, v11, s14, v123
	s_waitcnt lgkmcnt(2)
	v_fma_f32 v12, v12, s14, v124
	v_fma_f32 v13, v13, s14, v125
	s_waitcnt lgkmcnt(1)
	v_fma_f32 v14, v14, s14, v126
	v_fma_f32 v15, v15, s14, v127
	s_waitcnt lgkmcnt(0)
	v_fma_f32 v16, v16, s14, v128
	v_fma_f32 v17, v17, s14, v129
	ds_read2_b32 v[130:131], v223 offset0:0 offset1:1
	ds_read2_b32 v[132:133], v223 offset0:2 offset1:3
	ds_read2_b32 v[134:135], v223 offset0:4 offset1:5
	ds_read2_b32 v[136:137], v223 offset0:6 offset1:7
	ds_read2_b32 v[138:139], v223 offset0:16 offset1:17
	ds_read2_b32 v[140:141], v223 offset0:18 offset1:19
	ds_read2_b32 v[142:143], v223 offset0:20 offset1:21
	ds_read2_b32 v[144:145], v223 offset0:22 offset1:23
	s_waitcnt lgkmcnt(7)
	v_fma_f32 v18, v18, s14, v130
	v_fma_f32 v19, v19, s14, v131
	s_waitcnt lgkmcnt(6)
	v_fma_f32 v20, v20, s14, v132
	v_fma_f32 v21, v21, s14, v133
	s_waitcnt lgkmcnt(5)
	v_fma_f32 v22, v22, s14, v134
	v_fma_f32 v23, v23, s14, v135
	s_waitcnt lgkmcnt(4)
	v_fma_f32 v24, v24, s14, v136
	v_fma_f32 v25, v25, s14, v137
	s_waitcnt lgkmcnt(3)
	v_fma_f32 v26, v26, s14, v138
	v_fma_f32 v27, v27, s14, v139
	s_waitcnt lgkmcnt(2)
	v_fma_f32 v28, v28, s14, v140
	v_fma_f32 v29, v29, s14, v141
	s_waitcnt lgkmcnt(1)
	v_fma_f32 v30, v30, s14, v142
	v_fma_f32 v31, v31, s14, v143
	s_waitcnt lgkmcnt(0)
	v_fma_f32 v32, v32, s14, v144
	v_fma_f32 v33, v33, s14, v145
	ds_read2_b32 v[114:115], v224 offset0:0 offset1:1
	ds_read2_b32 v[116:117], v224 offset0:2 offset1:3
	ds_read2_b32 v[118:119], v224 offset0:4 offset1:5
	ds_read2_b32 v[120:121], v224 offset0:6 offset1:7
	ds_read2_b32 v[122:123], v224 offset0:16 offset1:17
	ds_read2_b32 v[124:125], v224 offset0:18 offset1:19
	ds_read2_b32 v[126:127], v224 offset0:20 offset1:21
	ds_read2_b32 v[128:129], v224 offset0:22 offset1:23
	s_waitcnt lgkmcnt(7)
	v_fma_f32 v34, v34, s14, v114
	v_fma_f32 v35, v35, s14, v115
	s_waitcnt lgkmcnt(6)
	v_fma_f32 v36, v36, s14, v116
	v_fma_f32 v37, v37, s14, v117
	s_waitcnt lgkmcnt(5)
	v_fma_f32 v38, v38, s14, v118
	v_fma_f32 v39, v39, s14, v119
	s_waitcnt lgkmcnt(4)
	v_fma_f32 v40, v40, s14, v120
	v_fma_f32 v41, v41, s14, v121
	s_waitcnt lgkmcnt(3)
	v_fma_f32 v42, v42, s14, v122
	v_fma_f32 v43, v43, s14, v123
	s_waitcnt lgkmcnt(2)
	v_fma_f32 v44, v44, s14, v124
	v_fma_f32 v45, v45, s14, v125
	s_waitcnt lgkmcnt(1)
	v_fma_f32 v46, v46, s14, v126
	v_fma_f32 v47, v47, s14, v127
	s_waitcnt lgkmcnt(0)
	v_fma_f32 v48, v48, s14, v128
	v_fma_f32 v49, v49, s14, v129
	v_max3_f32 v210, v2, v3, v4
	v_max3_f32 v219, v5, v6, v7
	v_max3_f32 v220, v8, v9, v10
	v_max3_f32 v221, v11, v12, v13
	v_max3_f32 v210, v210, v14, v15
	v_max3_f32 v219, v219, v16, v17
	v_max3_f32 v220, v220, v18, v19
	v_max3_f32 v221, v221, v20, v21
	v_max3_f32 v210, v210, v22, v23
	v_max3_f32 v219, v219, v24, v25
	v_max3_f32 v220, v220, v26, v27
	v_max3_f32 v221, v221, v28, v29
	v_max3_f32 v210, v210, v30, v31
	v_max3_f32 v219, v219, v32, v33
	v_max3_f32 v220, v220, v34, v35
	v_max3_f32 v221, v221, v36, v37
	v_max3_f32 v210, v210, v38, v39
	v_max3_f32 v219, v219, v40, v41
	v_max3_f32 v220, v220, v42, v43
	v_max3_f32 v221, v221, v44, v45
	v_max3_f32 v210, v210, v46, v47
	v_max3_f32 v219, v219, v48, v49
	v_max_f32_e32 v210, v210, v219
	v_max_f32_e32 v220, v220, v221
	v_max_f32_e32 v210, v210, v220
	v_mov_b32_e32 v219, v210
	s_nop 1
	v_permlane32_swap_b32_e32 v210, v219
	v_max_f32_e32 v210, v210, v219
	v_max_f32_e32 v210, v210, v209
	v_sub_f32_e32 v211, v209, v210
	v_exp_f32_e32 v211, v211
	v_mov_b32_e32 v209, v210
	v_mul_f32_e32 v50, v50, v211
	v_mul_f32_e32 v51, v51, v211
	v_mul_f32_e32 v52, v52, v211
	v_mul_f32_e32 v53, v53, v211
	v_mul_f32_e32 v54, v54, v211
	v_mul_f32_e32 v55, v55, v211
	v_mul_f32_e32 v56, v56, v211
	v_mul_f32_e32 v57, v57, v211
	v_mul_f32_e32 v58, v58, v211
	v_mul_f32_e32 v59, v59, v211
	v_mul_f32_e32 v60, v60, v211
	v_mul_f32_e32 v61, v61, v211
	v_mul_f32_e32 v62, v62, v211
	v_mul_f32_e32 v63, v63, v211
	v_mul_f32_e32 v64, v64, v211
	v_mul_f32_e32 v65, v65, v211
	v_mul_f32_e32 v66, v66, v211
	v_mul_f32_e32 v67, v67, v211
	v_mul_f32_e32 v68, v68, v211
	v_mul_f32_e32 v69, v69, v211
	v_mul_f32_e32 v70, v70, v211
	v_mul_f32_e32 v71, v71, v211
	v_mul_f32_e32 v72, v72, v211
	v_mul_f32_e32 v73, v73, v211
	v_mul_f32_e32 v74, v74, v211
	v_mul_f32_e32 v75, v75, v211
	v_mul_f32_e32 v76, v76, v211
	v_mul_f32_e32 v77, v77, v211
	v_mul_f32_e32 v78, v78, v211
	v_mul_f32_e32 v79, v79, v211
	v_mul_f32_e32 v80, v80, v211
	v_mul_f32_e32 v81, v81, v211
	v_mul_f32_e32 v212, v212, v211
	v_mov_b32_e32 v213, 0
	v_mov_b32_e32 v214, 0
	v_mov_b32_e32 v215, 0
	v_mov_b32_e32 v216, 0
	ds_read_b64_tr_b16 v[114:115], v201 offset:46080
	ds_read_b64_tr_b16 v[116:117], v201 offset:46656
	ds_read_b64_tr_b16 v[118:119], v201 offset:46144
	ds_read_b64_tr_b16 v[120:121], v201 offset:46720
	ds_read_b64_tr_b16 v[122:123], v201 offset:48384
	ds_read_b64_tr_b16 v[124:125], v201 offset:48960
	ds_read_b64_tr_b16 v[126:127], v201 offset:48448
	ds_read_b64_tr_b16 v[128:129], v201 offset:49024
	v_sub_f32_e32 v2, v2, v209
	v_sub_f32_e32 v3, v3, v209
	v_sub_f32_e32 v4, v4, v209
	v_sub_f32_e32 v5, v5, v209
	v_sub_f32_e32 v6, v6, v209
	v_sub_f32_e32 v7, v7, v209
	v_sub_f32_e32 v8, v8, v209
	v_sub_f32_e32 v9, v9, v209
	v_exp_f32_e32 v2, v2
	v_exp_f32_e32 v3, v3
	v_exp_f32_e32 v4, v4
	v_exp_f32_e32 v5, v5
	v_exp_f32_e32 v6, v6
	v_exp_f32_e32 v7, v7
	v_exp_f32_e32 v8, v8
	v_exp_f32_e32 v9, v9
	v_add_f32_e32 v213, v213, v2
	v_add_f32_e32 v214, v214, v3
	v_add_f32_e32 v215, v215, v4
	v_add_f32_e32 v216, v216, v5
	v_add_f32_e32 v213, v213, v6
	v_add_f32_e32 v214, v214, v7
	v_add_f32_e32 v215, v215, v8
	v_add_f32_e32 v216, v216, v9
	v_cvt_pk_bf16_f32 v2, v2, v3
	v_cvt_pk_bf16_f32 v3, v4, v5
	v_cvt_pk_bf16_f32 v4, v6, v7
	v_cvt_pk_bf16_f32 v5, v8, v9
	ds_read_b64_tr_b16 v[130:131], v243 offset:9216
	ds_read_b64_tr_b16 v[132:133], v243 offset:9792
	ds_read_b64_tr_b16 v[134:135], v243 offset:9280
	ds_read_b64_tr_b16 v[136:137], v243 offset:9856
	s_waitcnt lgkmcnt(10)
	v_mfma_f32_32x32x16_bf16 v[50:65], v[114:117], v[2:5], v[50:65]
	s_waitcnt lgkmcnt(8)
	v_mfma_f32_32x32x16_bf16 v[66:81], v[118:121], v[2:5], v[66:81]
	v_sub_f32_e32 v10, v10, v209
	v_sub_f32_e32 v11, v11, v209
	v_sub_f32_e32 v12, v12, v209
	v_sub_f32_e32 v13, v13, v209
	v_sub_f32_e32 v14, v14, v209
	v_sub_f32_e32 v15, v15, v209
	v_sub_f32_e32 v16, v16, v209
	v_sub_f32_e32 v17, v17, v209
	v_exp_f32_e32 v10, v10
	v_exp_f32_e32 v11, v11
	v_exp_f32_e32 v12, v12
	v_exp_f32_e32 v13, v13
	v_exp_f32_e32 v14, v14
	v_exp_f32_e32 v15, v15
	v_exp_f32_e32 v16, v16
	v_exp_f32_e32 v17, v17
	v_add_f32_e32 v213, v213, v10
	v_add_f32_e32 v214, v214, v11
	v_add_f32_e32 v215, v215, v12
	v_add_f32_e32 v216, v216, v13
	v_add_f32_e32 v213, v213, v14
	v_add_f32_e32 v214, v214, v15
	v_add_f32_e32 v215, v215, v16
	v_add_f32_e32 v216, v216, v17
	v_cvt_pk_bf16_f32 v10, v10, v11
	v_cvt_pk_bf16_f32 v11, v12, v13
	v_cvt_pk_bf16_f32 v12, v14, v15
	v_cvt_pk_bf16_f32 v13, v16, v17
	ds_read_b64_tr_b16 v[138:139], v243 offset:11520
	ds_read_b64_tr_b16 v[140:141], v243 offset:12096
	ds_read_b64_tr_b16 v[142:143], v243 offset:11584
	ds_read_b64_tr_b16 v[144:145], v243 offset:12160
	s_waitcnt lgkmcnt(10)
	v_mfma_f32_32x32x16_bf16 v[50:65], v[122:125], v[10:13], v[50:65]
	s_waitcnt lgkmcnt(8)
	v_mfma_f32_32x32x16_bf16 v[66:81], v[126:129], v[10:13], v[66:81]
	v_sub_f32_e32 v18, v18, v209
	v_sub_f32_e32 v19, v19, v209
	v_sub_f32_e32 v20, v20, v209
	v_sub_f32_e32 v21, v21, v209
	v_sub_f32_e32 v22, v22, v209
	v_sub_f32_e32 v23, v23, v209
	v_sub_f32_e32 v24, v24, v209
	v_sub_f32_e32 v25, v25, v209
	v_exp_f32_e32 v18, v18
	v_exp_f32_e32 v19, v19
	v_exp_f32_e32 v20, v20
	v_exp_f32_e32 v21, v21
	v_exp_f32_e32 v22, v22
	v_exp_f32_e32 v23, v23
	v_exp_f32_e32 v24, v24
	v_exp_f32_e32 v25, v25
	v_add_f32_e32 v213, v213, v18
	v_add_f32_e32 v214, v214, v19
	v_add_f32_e32 v215, v215, v20
	v_add_f32_e32 v216, v216, v21
	v_add_f32_e32 v213, v213, v22
	v_add_f32_e32 v214, v214, v23
	v_add_f32_e32 v215, v215, v24
	v_add_f32_e32 v216, v216, v25
	v_cvt_pk_bf16_f32 v18, v18, v19
	v_cvt_pk_bf16_f32 v19, v20, v21
	v_cvt_pk_bf16_f32 v20, v22, v23
	v_cvt_pk_bf16_f32 v21, v24, v25
	ds_read_b64_tr_b16 v[114:115], v243 offset:27648
	ds_read_b64_tr_b16 v[116:117], v243 offset:28224
	ds_read_b64_tr_b16 v[118:119], v243 offset:27712
	ds_read_b64_tr_b16 v[120:121], v243 offset:28288
	s_waitcnt lgkmcnt(10)
	v_mfma_f32_32x32x16_bf16 v[50:65], v[130:133], v[18:21], v[50:65]
	s_waitcnt lgkmcnt(8)
	v_mfma_f32_32x32x16_bf16 v[66:81], v[134:137], v[18:21], v[66:81]
	v_sub_f32_e32 v26, v26, v209
	v_sub_f32_e32 v27, v27, v209
	v_sub_f32_e32 v28, v28, v209
	v_sub_f32_e32 v29, v29, v209
	v_sub_f32_e32 v30, v30, v209
	v_sub_f32_e32 v31, v31, v209
	v_sub_f32_e32 v32, v32, v209
	v_sub_f32_e32 v33, v33, v209
	v_exp_f32_e32 v26, v26
	v_exp_f32_e32 v27, v27
	v_exp_f32_e32 v28, v28
	v_exp_f32_e32 v29, v29
	v_exp_f32_e32 v30, v30
	v_exp_f32_e32 v31, v31
	v_exp_f32_e32 v32, v32
	v_exp_f32_e32 v33, v33
	v_add_f32_e32 v213, v213, v26
	v_add_f32_e32 v214, v214, v27
	v_add_f32_e32 v215, v215, v28
	v_add_f32_e32 v216, v216, v29
	v_add_f32_e32 v213, v213, v30
	v_add_f32_e32 v214, v214, v31
	v_add_f32_e32 v215, v215, v32
	v_add_f32_e32 v216, v216, v33
	v_cvt_pk_bf16_f32 v26, v26, v27
	v_cvt_pk_bf16_f32 v27, v28, v29
	v_cvt_pk_bf16_f32 v28, v30, v31
	v_cvt_pk_bf16_f32 v29, v32, v33
	ds_read_b64_tr_b16 v[122:123], v243 offset:29952
	ds_read_b64_tr_b16 v[124:125], v243 offset:30528
	ds_read_b64_tr_b16 v[126:127], v243 offset:30016
	ds_read_b64_tr_b16 v[128:129], v243 offset:30592
	s_waitcnt lgkmcnt(10)
	v_mfma_f32_32x32x16_bf16 v[50:65], v[138:141], v[26:29], v[50:65]
	s_waitcnt lgkmcnt(8)
	v_mfma_f32_32x32x16_bf16 v[66:81], v[142:145], v[26:29], v[66:81]
	v_sub_f32_e32 v34, v34, v209
	v_sub_f32_e32 v35, v35, v209
	v_sub_f32_e32 v36, v36, v209
	v_sub_f32_e32 v37, v37, v209
	v_sub_f32_e32 v38, v38, v209
	v_sub_f32_e32 v39, v39, v209
	v_sub_f32_e32 v40, v40, v209
	v_sub_f32_e32 v41, v41, v209
	v_exp_f32_e32 v34, v34
	v_exp_f32_e32 v35, v35
	v_exp_f32_e32 v36, v36
	v_exp_f32_e32 v37, v37
	v_exp_f32_e32 v38, v38
	v_exp_f32_e32 v39, v39
	v_exp_f32_e32 v40, v40
	v_exp_f32_e32 v41, v41
	v_add_f32_e32 v213, v213, v34
	v_add_f32_e32 v214, v214, v35
	v_add_f32_e32 v215, v215, v36
	v_add_f32_e32 v216, v216, v37
	v_add_f32_e32 v213, v213, v38
	v_add_f32_e32 v214, v214, v39
	v_add_f32_e32 v215, v215, v40
	v_add_f32_e32 v216, v216, v41
	v_cvt_pk_bf16_f32 v34, v34, v35
	v_cvt_pk_bf16_f32 v35, v36, v37
	v_cvt_pk_bf16_f32 v36, v38, v39
	v_cvt_pk_bf16_f32 v37, v40, v41
	s_waitcnt lgkmcnt(6)
	s_nop 0
	v_mfma_f32_32x32x16_bf16 v[50:65], v[114:117], v[34:37], v[50:65]
	s_waitcnt lgkmcnt(4)
	v_mfma_f32_32x32x16_bf16 v[66:81], v[118:121], v[34:37], v[66:81]
	v_sub_f32_e32 v42, v42, v209
	v_sub_f32_e32 v43, v43, v209
	v_sub_f32_e32 v44, v44, v209
	v_sub_f32_e32 v45, v45, v209
	v_sub_f32_e32 v46, v46, v209
	v_sub_f32_e32 v47, v47, v209
	v_sub_f32_e32 v48, v48, v209
	v_sub_f32_e32 v49, v49, v209
	v_exp_f32_e32 v42, v42
	v_exp_f32_e32 v43, v43
	v_exp_f32_e32 v44, v44
	v_exp_f32_e32 v45, v45
	v_exp_f32_e32 v46, v46
	v_exp_f32_e32 v47, v47
	v_exp_f32_e32 v48, v48
	v_exp_f32_e32 v49, v49
	v_add_f32_e32 v213, v213, v42
	v_add_f32_e32 v214, v214, v43
	v_add_f32_e32 v215, v215, v44
	v_add_f32_e32 v216, v216, v45
	v_add_f32_e32 v213, v213, v46
	v_add_f32_e32 v214, v214, v47
	v_add_f32_e32 v215, v215, v48
	v_add_f32_e32 v216, v216, v49
	v_cvt_pk_bf16_f32 v42, v42, v43
	v_cvt_pk_bf16_f32 v43, v44, v45
	v_cvt_pk_bf16_f32 v44, v46, v47
	v_cvt_pk_bf16_f32 v45, v48, v49
	s_waitcnt lgkmcnt(2)
	s_nop 0
	v_mfma_f32_32x32x16_bf16 v[50:65], v[122:125], v[42:45], v[50:65]
	s_waitcnt lgkmcnt(0)
	v_mfma_f32_32x32x16_bf16 v[66:81], v[126:129], v[42:45], v[66:81]
	v_add_f32_e32 v213, v213, v214
	v_add_f32_e32 v215, v215, v216
	v_add_f32_e32 v213, v213, v215
	v_add_f32_e32 v212, v212, v213
